# cross-attention K and V tiles staged by direct HBM-to-LDS loads (source-side XOR swizzle) instead of load-to-VGPR plus ds_write
# baseline (speedup 1.0000x reference)
; #define LAS __attribute__((address_space(3)))
;     __host__ __device__ bool next(int i, Unit& u) const {
;         const long L = (long)i * G + c; if (L >= nwg) return false;
;         int wgid = (int)L; { constexpr int q = nwg / NXCD, r = nwg % NXCD; const int xcd = wgid % NXCD, off = wgid / NXCD; wgid = (xcd < r ? xcd * (q + 1) : r * (q + 1) + (xcd - r) * q) + off; }
;         constexpr int nig = WGM * nN; const int gid = wgid / nig, fm = gid * WGM, gsz = (nM - fm) < WGM ? (nM - fm) : WGM;
;         u.pm = fm + ((wgid % nig) % gsz); u.pn = (wgid % nig) / gsz; return true;
;     }
; __device__ __forceinline__ void att_stage(LAS unsigned char* lds, const bf16_t* src, int pitch, int tid) {
;     const int r0 = tid >> 5, ch = tid & 31;
;     const bf16_t* g0 = src + (size_t)r0 * pitch + ch * 8;
;     LAS unsigned char* l0 = lds + r0 * 512 + ((ch ^ r0) << 4);
;     u32x4 v[16];
; #pragma unroll
;     for (int x = 0; x < 16; ++x) v[x] = *(const u32x4*)(g0 + (size_t)(16 * x) * pitch);
; #pragma unroll
;     for (int x = 0; x < 16; ++x) *(LAS u32x4*)(l0 + x * 8192) = v[x];
; }
; template <class Sched> __device__ __forceinline__ void att_phase(LAS unsigned char* lds, const bf16_t* Kl, const bf16_t* Vl, const bf16_t* Qb, bf16_t* Ob, const Sched& S, int tid) {
;     pg8::Unit un;
;     for (int ui = 0; S.next(ui, un); ++ui) {
;         asm volatile("" : "+v"(tid));
;         const int lane = tid & 63, wave = __builtin_amdgcn_readfirstlane(tid >> 6), j = lane & 15, kg = lane >> 4;
;         const int h = un.pn, pm = un.pm, b = pm >> 5;
;         att_stage(lds, Kl + (size_t)(b * 256) * 4096 + h * 256, 4096, tid);
;         const bf16_t* qrow = Qb + (size_t)(pm * 256 + 16 * wave + j) * 1024 + h * 256;
;         bf16_t* orow = Ob + (size_t)(pm * 256 + 16 * wave + j) * 1024 + h * 256;
;         __syncthreads();
.LBB0_124:
	s_add_i32 s4, s7, s4
	s_ashr_i32 s5, s4, 31
	s_lshr_b32 s5, s5, 27
	s_add_i32 s5, s4, s5
	s_ashr_i32 s6, s5, 5
	s_lshl_b32 s6, s6, 3
	s_sub_i32 s7, 0x80, s6
	s_min_i32 s7, s7, 8
	s_abs_i32 s10, s7
	v_cvt_f32_u32_e32 v0, s10
	s_sub_i32 s12, 0, s10
	s_andn2_b32 s5, s5, 31
	s_sub_i32 s4, s4, s5
	v_rcp_iflag_f32_e32 v0, v0
	s_abs_i32 s5, s4
	s_xor_b32 s11, s4, s7
	s_ashr_i32 s11, s11, 31
	v_mul_f32_e32 v0, 0x4f7ffffe, v0
	v_cvt_u32_f32_e32 v0, v0
	s_mov_b32 s16, 0x20000
	v_ashrrev_i32_e32 v108, 5, v114
	v_readfirstlane_b32 s13, v0
	s_mul_i32 s12, s12, s13
	s_mul_hi_u32 s12, s13, s12
	s_add_i32 s13, s13, s12
	s_mul_hi_u32 s12, s5, s13
	s_mul_i32 s13, s12, s10
	s_sub_i32 s5, s5, s13
	s_add_i32 s14, s12, 1
	s_sub_i32 s13, s5, s10
	s_cmp_ge_u32 s5, s10
	s_cselect_b32 s12, s14, s12
	s_cselect_b32 s5, s13, s5
	s_add_i32 s13, s12, 1
	s_cmp_ge_u32 s5, s10
	s_cselect_b32 s5, s13, s12
	s_xor_b32 s5, s5, s11
	s_sub_i32 s10, s5, s11
	s_mul_i32 s5, s10, s7
	s_sub_i32 s4, s4, s5
	s_add_i32 s14, s6, s4
	s_lshl_b32 s4, s14, 3
	s_and_b32 s4, s4, 0xffffff00
	s_ashr_i32 s5, s4, 31
	s_lshl_b64 s[6:7], s[4:5], 13
	v_readlane_b32 s11, v254, 20
	s_add_u32 s6, s11, s6
	v_readlane_b32 s11, v254, 21
	s_addc_u32 s7, s11, s7
	s_lshl_b32 s10, s10, 8
	s_ashr_i32 s11, s10, 31
	s_lshl_b64 s[12:13], s[10:11], 1
	s_add_u32 s6, s6, s12
	v_ashrrev_i32_e32 v109, 31, v108
	s_addc_u32 s7, s7, s13
	v_bitop3_b32 v2, v114, v108, 31 bitop3:0x6c
	v_lshlrev_b64 v[0:1], 13, v[108:109]
	v_lshl_add_u64 v[0:1], s[6:7], 0, v[0:1]
	v_lshlrev_b32_e32 v164, 4, v2
	v_lshl_add_u64 v[0:1], v[0:1], 0, v[164:165]
	v_readfirstlane_b32 s15, v114
	s_nop 1
	s_lshl_b32 s15, s15, 4
	s_mov_b32 m0, s15
	v_add_co_u32_e32 v6, vcc, s16, v0
	s_mov_b32 s15, 0x40000
	s_nop 0
	v_addc_co_u32_e32 v7, vcc, 0, v1, vcc
	v_add_co_u32_e32 v10, vcc, s15, v0
	s_mov_b32 s17, 0x60000
	s_nop 0
	v_addc_co_u32_e32 v11, vcc, 0, v1, vcc
	v_add_co_u32_e32 v14, vcc, s17, v0
	s_mov_b32 s6, 0x80000
	s_nop 0
	v_addc_co_u32_e32 v15, vcc, 0, v1, vcc
	v_add_co_u32_e32 v18, vcc, s6, v0
	s_mov_b32 s6, 0xa0000
	s_nop 0
	v_addc_co_u32_e32 v19, vcc, 0, v1, vcc
	v_add_co_u32_e32 v22, vcc, s6, v0
	s_mov_b32 s6, 0xc0000
	s_nop 0
	v_addc_co_u32_e32 v23, vcc, 0, v1, vcc
	v_add_co_u32_e32 v26, vcc, s6, v0
	s_mov_b32 s6, 0xe0000
	s_nop 0
	v_addc_co_u32_e32 v27, vcc, 0, v1, vcc
	v_add_co_u32_e32 v30, vcc, s6, v0
	s_mov_b32 s6, 0x100000
	s_nop 0
	v_addc_co_u32_e32 v31, vcc, 0, v1, vcc
	v_add_co_u32_e32 v34, vcc, s6, v0
	s_mov_b32 s6, 0x120000
	s_nop 0
	v_addc_co_u32_e32 v35, vcc, 0, v1, vcc
	v_add_co_u32_e32 v38, vcc, s6, v0
	s_mov_b32 s6, 0x140000
	s_nop 0
	v_addc_co_u32_e32 v39, vcc, 0, v1, vcc
	v_add_co_u32_e32 v42, vcc, s6, v0
	s_mov_b32 s6, 0x160000
	s_nop 0
	v_addc_co_u32_e32 v43, vcc, 0, v1, vcc
	v_add_co_u32_e32 v46, vcc, s6, v0
	s_mov_b32 s6, 0x180000
	s_nop 0
	v_addc_co_u32_e32 v47, vcc, 0, v1, vcc
	v_add_co_u32_e32 v50, vcc, s6, v0
	s_mov_b32 s6, 0x1a0000
	s_nop 0
	v_addc_co_u32_e32 v51, vcc, 0, v1, vcc
	global_load_lds_dwordx4 v[0:1], off
	s_nop 0
	s_add_i32 m0, m0, 0x2000
	s_nop 0
	global_load_lds_dwordx4 v[6:7], off
	s_nop 0
	s_add_i32 m0, m0, 0x2000
	s_nop 0
	global_load_lds_dwordx4 v[10:11], off
	s_nop 0
	s_add_i32 m0, m0, 0x2000
	s_nop 0
	global_load_lds_dwordx4 v[14:15], off
	s_nop 0
	s_add_i32 m0, m0, 0x2000
	s_nop 0
	global_load_lds_dwordx4 v[18:19], off
	s_nop 0
	s_add_i32 m0, m0, 0x2000
	s_nop 0
	global_load_lds_dwordx4 v[22:23], off
	s_nop 0
	s_add_i32 m0, m0, 0x2000
	s_nop 0
	global_load_lds_dwordx4 v[26:27], off
	s_nop 0
	s_add_i32 m0, m0, 0x2000
	s_nop 0
	global_load_lds_dwordx4 v[30:31], off
	v_add_co_u32_e32 v54, vcc, s6, v0
	s_mov_b32 s6, 0x1c0000
	s_nop 0
	v_addc_co_u32_e32 v55, vcc, 0, v1, vcc
	v_add_co_u32_e32 v58, vcc, s6, v0
	s_mov_b32 s6, 0x1e0000
	s_nop 0
	v_addc_co_u32_e32 v59, vcc, 0, v1, vcc
	v_add_co_u32_e32 v0, vcc, s6, v0
	s_add_i32 m0, m0, 0x2000
	s_nop 0
	global_load_lds_dwordx4 v[34:35], off
	s_nop 0
	s_add_i32 m0, m0, 0x2000
	s_nop 0
	global_load_lds_dwordx4 v[38:39], off
	s_nop 0
	s_add_i32 m0, m0, 0x2000
	s_nop 0
	global_load_lds_dwordx4 v[42:43], off
	s_nop 0
	s_add_i32 m0, m0, 0x2000
	s_nop 0
	global_load_lds_dwordx4 v[46:47], off
	s_nop 0
	s_add_i32 m0, m0, 0x2000
	s_nop 0
	global_load_lds_dwordx4 v[50:51], off
	s_nop 0
	s_add_i32 m0, m0, 0x2000
	s_nop 0
	global_load_lds_dwordx4 v[54:55], off
	v_addc_co_u32_e32 v1, vcc, 0, v1, vcc
	s_add_i32 m0, m0, 0x2000
	s_nop 0
	global_load_lds_dwordx4 v[58:59], off
	v_readfirstlane_b32 s6, v114
	s_add_i32 m0, m0, 0x2000
	s_nop 0
	global_load_lds_dwordx4 v[0:1], off
	v_bitop3_b32 v67, v114, v108, 31 bitop3:0x6c
	s_ashr_i32 s6, s6, 2
	v_lshlrev_b32_e32 v66, 9, v108
	v_lshlrev_b32_e32 v67, 4, v67
	s_lshl_b32 s7, s14, 8
	s_and_b32 s6, s6, -16
	v_and_b32_e32 v1, 15, v114
	v_add3_u32 v130, 0, v66, v67
	s_add_i32 s6, s6, s7
	v_or_b32_e32 v2, s6, v1
	v_ashrrev_i32_e32 v3, 31, v2
	v_readlane_b32 s6, v252, 36
	v_lshlrev_b64 v[2:3], 11, v[2:3]
	v_readlane_b32 s7, v252, 37
	v_bfe_u32 v0, v114, 4, 2
	v_add_u32_e32 v137, 0x1c000, v130
	v_lshl_add_u64 v[2:3], s[6:7], 0, v[2:3]
	v_lshl_add_u64 v[106:107], v[2:3], 0, s[12:13]
	v_lshlrev_b32_e32 v2, 4, v0
	v_mov_b32_e32 v3, v165
	v_add_u32_e32 v131, 0x10000, v130
	v_add_u32_e32 v132, 0x12000, v130
	v_add_u32_e32 v133, 0x14000, v130
	v_add_u32_e32 v134, 0x16000, v130
	v_add_u32_e32 v135, 0x18000, v130
	v_add_u32_e32 v136, 0x1a000, v130
	v_add_u32_e32 v138, 0x1e000, v130
	v_lshl_add_u64 v[58:59], v[106:107], 0, v[2:3]
	s_waitcnt vmcnt(0)
	s_waitcnt lgkmcnt(0)
	s_barrier
; #define LAS __attribute__((address_space(3)))
; template <class Sched> __device__ __forceinline__ void att_phase(LAS unsigned char* lds, const bf16_t* Kl, const bf16_t* Vl, const bf16_t* Qb, bf16_t* Ob, const Sched& S, int tid) {
;     ...
;         for (int hf = 0; hf < 2; ++hf) {
;             bf16x8_t qf[8];
; #pragma unroll
;             for (int s = 0; s < 8; ++s) qf[s] = *(const bf16x8_t*)(qrow + (size_t)hf * 128 * 1024 + 32 * s + 8 * kg);
;             f32x4 acc[16];
; #pragma unroll
;             for (int kb = 0; kb < 16; ++kb) acc[kb] = (f32x4){0.f, 0.f, 0.f, 0.f};
; #pragma unroll
;             for (int s = 0; s < 8; ++s)
; #pragma unroll
;                 for (int kb = 0; kb < 16; ++kb) { const bf16x8_t af = *(const LAS bf16x8_t*)(fbase + kb * 8192 + (((4 * s + kg) ^ j) << 4));
;                     acc[kb] = __builtin_amdgcn_mfma_f32_16x16x32_bf16(af, qf[s], acc[kb], 0, 0, 0); }
	global_load_dwordx4 v[2:5], v[58:59], off
	v_lshrrev_b32_e32 v6, 4, v114
	v_bitop3_b32 v6, v6, v1, 3 bitop3:0x6c
	v_lshl_add_u32 v115, v1, 9, 0
	v_lshlrev_b32_e32 v116, 4, v6
	v_add_u32_e32 v124, v115, v116
	ds_read_b128 v[6:9], v124
	ds_read_b128 v[10:13], v124 offset:8192
	global_load_dwordx4 v[14:17], v[58:59], off offset:64
	v_add_u32_e32 v161, 0x10000, v124
	v_add_u32_e32 v160, 0x12000, v124
	v_add_u32_e32 v159, 0x14000, v124
	v_add_u32_e32 v158, 0x16000, v124
	v_add_u32_e32 v157, 0x18000, v124
	v_add_u32_e32 v156, 0x1a000, v124
	v_add_u32_e32 v155, 0x1c000, v124
	v_add_u32_e32 v154, 0x1e000, v124
	ds_read_b128 v[18:21], v124 offset:16384
	ds_read_b128 v[22:25], v124 offset:24576
	ds_read_b128 v[26:29], v124 offset:32768
	ds_read_b128 v[30:33], v124 offset:40960
	ds_read_b128 v[34:37], v124 offset:49152
	ds_read_b128 v[38:41], v124 offset:57344
	ds_read_b128 v[42:45], v161
	ds_read_b128 v[46:49], v160
	ds_read_b128 v[50:53], v159
	ds_read_b128 v[54:57], v158
	ds_read_b128 v[60:63], v157
	ds_read_b128 v[64:67], v156
	ds_read_b128 v[68:71], v155
	ds_read_b128 v[72:75], v154
	v_bitop3_b32 v76, v0, v1, 4 bitop3:0x36
	v_lshlrev_b32_e32 v117, 4, v76
	v_add_u32_e32 v125, v115, v117
	s_waitcnt vmcnt(1) lgkmcnt(14)
	v_mfma_f32_16x16x32_bf16 v[6:9], v[6:9], v[2:5], 0
	ds_read_b128 v[76:79], v125
	v_add_u32_e32 v153, 0x10000, v125
	v_add_u32_e32 v152, 0x12000, v125
	v_mfma_f32_16x16x32_bf16 v[10:13], v[10:13], v[2:5], 0
	v_add_u32_e32 v151, 0x14000, v125
	v_add_u32_e32 v150, 0x16000, v125
	v_add_u32_e32 v149, 0x18000, v125
	s_waitcnt lgkmcnt(14)
	v_mfma_f32_16x16x32_bf16 v[18:21], v[18:21], v[2:5], 0
	v_add_u32_e32 v148, 0x1a000, v125
	v_add_u32_e32 v147, 0x1c000, v125
	v_add_u32_e32 v146, 0x1e000, v125
	s_waitcnt lgkmcnt(13)
	v_mfma_f32_16x16x32_bf16 v[22:25], v[22:25], v[2:5], 0
	v_lshlrev_b32_e32 v110, 3, v0
	v_mov_b32_e32 v111, v165
	s_waitcnt lgkmcnt(12)
	v_mfma_f32_16x16x32_bf16 v[26:29], v[26:29], v[2:5], 0
	s_waitcnt lgkmcnt(11)
	v_mfma_f32_16x16x32_bf16 v[30:33], v[30:33], v[2:5], 0
	s_waitcnt lgkmcnt(10)
	v_mfma_f32_16x16x32_bf16 v[34:37], v[34:37], v[2:5], 0
	s_waitcnt lgkmcnt(9)
	v_mfma_f32_16x16x32_bf16 v[38:41], v[38:41], v[2:5], 0
	s_waitcnt lgkmcnt(8)
	v_mfma_f32_16x16x32_bf16 v[42:45], v[42:45], v[2:5], 0
	s_waitcnt lgkmcnt(7)
	v_mfma_f32_16x16x32_bf16 v[46:49], v[46:49], v[2:5], 0
	s_waitcnt lgkmcnt(6)
	v_mfma_f32_16x16x32_bf16 v[50:53], v[50:53], v[2:5], 0
	s_waitcnt lgkmcnt(5)
	v_mfma_f32_16x16x32_bf16 v[54:57], v[54:57], v[2:5], 0
	s_waitcnt lgkmcnt(4)
	v_mfma_f32_16x16x32_bf16 v[60:63], v[60:63], v[2:5], 0
	s_waitcnt lgkmcnt(3)
	v_mfma_f32_16x16x32_bf16 v[64:67], v[64:67], v[2:5], 0
	s_waitcnt lgkmcnt(2)
	v_mfma_f32_16x16x32_bf16 v[68:71], v[68:71], v[2:5], 0
	s_waitcnt lgkmcnt(1)
	v_mfma_f32_16x16x32_bf16 v[2:5], v[72:75], v[2:5], 0
	ds_read_b128 v[72:75], v125 offset:8192
	s_waitcnt vmcnt(0) lgkmcnt(1)
	v_mfma_f32_16x16x32_bf16 v[6:9], v[76:79], v[14:17], v[6:9]
	ds_read_b128 v[76:79], v125 offset:16384
	s_waitcnt lgkmcnt(1)
	v_mfma_f32_16x16x32_bf16 v[10:13], v[72:75], v[14:17], v[10:13]
	ds_read_b128 v[72:75], v125 offset:24576
	s_waitcnt lgkmcnt(1)
	v_mfma_f32_16x16x32_bf16 v[18:21], v[76:79], v[14:17], v[18:21]
	s_waitcnt lgkmcnt(0)
	v_mfma_f32_16x16x32_bf16 v[22:25], v[72:75], v[14:17], v[22:25]
	ds_read_b128 v[72:75], v125 offset:32768
	ds_read_b128 v[76:79], v125 offset:40960
	s_waitcnt lgkmcnt(1)
	v_mfma_f32_16x16x32_bf16 v[26:29], v[72:75], v[14:17], v[26:29]
	global_load_dwordx4 v[72:75], v[58:59], off offset:128
	s_waitcnt lgkmcnt(0)
	v_mfma_f32_16x16x32_bf16 v[30:33], v[76:79], v[14:17], v[30:33]
	ds_read_b128 v[76:79], v125 offset:49152
	ds_read_b128 v[80:83], v125 offset:57344
	s_waitcnt lgkmcnt(1)
	v_mfma_f32_16x16x32_bf16 v[34:37], v[76:79], v[14:17], v[34:37]
	ds_read_b128 v[76:79], v153
	s_waitcnt lgkmcnt(1)
	v_mfma_f32_16x16x32_bf16 v[38:41], v[80:83], v[14:17], v[38:41]
	ds_read_b128 v[80:83], v152
	s_waitcnt lgkmcnt(1)
	v_mfma_f32_16x16x32_bf16 v[42:45], v[76:79], v[14:17], v[42:45]
	ds_read_b128 v[76:79], v151
	s_waitcnt lgkmcnt(1)
	v_mfma_f32_16x16x32_bf16 v[46:49], v[80:83], v[14:17], v[46:49]
	ds_read_b128 v[80:83], v150
	s_waitcnt lgkmcnt(1)
	v_mfma_f32_16x16x32_bf16 v[50:53], v[76:79], v[14:17], v[50:53]
	ds_read_b128 v[76:79], v149
	s_waitcnt lgkmcnt(1)
	v_mfma_f32_16x16x32_bf16 v[54:57], v[80:83], v[14:17], v[54:57]
	ds_read_b128 v[80:83], v148
	s_waitcnt lgkmcnt(1)
	v_mfma_f32_16x16x32_bf16 v[60:63], v[76:79], v[14:17], v[60:63]
	ds_read_b128 v[76:79], v147
	s_waitcnt lgkmcnt(1)
	v_mfma_f32_16x16x32_bf16 v[64:67], v[80:83], v[14:17], v[64:67]
	ds_read_b128 v[80:83], v146
	s_waitcnt lgkmcnt(1)
	v_mfma_f32_16x16x32_bf16 v[68:71], v[76:79], v[14:17], v[68:71]
	v_bitop3_b32 v76, v0, v1, 8 bitop3:0x36
	v_lshlrev_b32_e32 v118, 4, v76
	v_add_u32_e32 v126, v115, v118
	s_waitcnt lgkmcnt(0)
	v_mfma_f32_16x16x32_bf16 v[2:5], v[80:83], v[14:17], v[2:5]
	global_load_dwordx4 v[80:83], v[58:59], off offset:192
	ds_read_b128 v[76:79], v126
	ds_read_b128 v[14:17], v126 offset:8192
	s_waitcnt vmcnt(1) lgkmcnt(1)
	v_mfma_f32_16x16x32_bf16 v[6:9], v[76:79], v[72:75], v[6:9]
	ds_read_b128 v[76:79], v126 offset:16384
	v_add_u32_e32 v145, 0x10000, v126
	v_add_u32_e32 v144, 0x12000, v126
	s_waitcnt lgkmcnt(1)
	v_mfma_f32_16x16x32_bf16 v[10:13], v[14:17], v[72:75], v[10:13]
	ds_read_b128 v[14:17], v126 offset:24576
	v_add_u32_e32 v113, 0x14000, v126
	v_add_u32_e32 v112, 0x16000, v126
	s_waitcnt lgkmcnt(1)
	v_mfma_f32_16x16x32_bf16 v[18:21], v[76:79], v[72:75], v[18:21]
	ds_read_b128 v[76:79], v126 offset:32768
	v_add_u32_e32 v105, 0x18000, v126
	v_add_u32_e32 v104, 0x1a000, v126
	s_waitcnt lgkmcnt(1)
; #define LAS __attribute__((address_space(3)))
; template <class Sched> __device__ __forceinline__ void att_phase(LAS unsigned char* lds, const bf16_t* Kl, const bf16_t* Vl, const bf16_t* Qb, bf16_t* Ob, const Sched& S, int tid) {
;     ...
;             for (int s = 0; s < 8; ++s)
; #pragma unroll
;                 for (int kb = 0; kb < 16; ++kb) { const bf16x8_t af = *(const LAS bf16x8_t*)(fbase + kb * 8192 + (((4 * s + kg) ^ j) << 4));
;                     acc[kb] = __builtin_amdgcn_mfma_f32_16x16x32_bf16(af, qf[s], acc[kb], 0, 0, 0); }
	v_mfma_f32_16x16x32_bf16 v[14:17], v[14:17], v[72:75], v[22:25]
	v_add_u32_e32 v103, 0x1c000, v126
	v_add_u32_e32 v102, 0x1e000, v126
	s_nop 0
	ds_read_b128 v[22:25], v126 offset:40960
	s_waitcnt lgkmcnt(1)
	v_mfma_f32_16x16x32_bf16 v[26:29], v[76:79], v[72:75], v[26:29]
	s_waitcnt lgkmcnt(0)
	v_mfma_f32_16x16x32_bf16 v[22:25], v[22:25], v[72:75], v[30:33]
	s_nop 2
	ds_read_b128 v[30:33], v126 offset:49152
	ds_read_b128 v[76:79], v126 offset:57344
	s_waitcnt lgkmcnt(1)
	v_mfma_f32_16x16x32_bf16 v[30:33], v[30:33], v[72:75], v[34:37]
	s_nop 2
	ds_read_b128 v[34:37], v145
	s_waitcnt lgkmcnt(1)
	v_mfma_f32_16x16x32_bf16 v[38:41], v[76:79], v[72:75], v[38:41]
	ds_read_b128 v[76:79], v144
	s_waitcnt lgkmcnt(1)
	v_mfma_f32_16x16x32_bf16 v[34:37], v[34:37], v[72:75], v[42:45]
	s_nop 2
	ds_read_b128 v[42:45], v113
	s_waitcnt lgkmcnt(1)
	v_mfma_f32_16x16x32_bf16 v[46:49], v[76:79], v[72:75], v[46:49]
	ds_read_b128 v[76:79], v112
	s_waitcnt lgkmcnt(1)
	v_mfma_f32_16x16x32_bf16 v[42:45], v[42:45], v[72:75], v[50:53]
	s_nop 2
	ds_read_b128 v[50:53], v105
	s_waitcnt lgkmcnt(1)
	v_mfma_f32_16x16x32_bf16 v[54:57], v[76:79], v[72:75], v[54:57]
	ds_read_b128 v[76:79], v104
	s_waitcnt lgkmcnt(1)
	v_mfma_f32_16x16x32_bf16 v[50:53], v[50:53], v[72:75], v[60:63]
	s_nop 2
	ds_read_b128 v[60:63], v103
	s_waitcnt lgkmcnt(1)
	v_mfma_f32_16x16x32_bf16 v[64:67], v[76:79], v[72:75], v[64:67]
	ds_read_b128 v[76:79], v102
	s_waitcnt lgkmcnt(1)
	v_mfma_f32_16x16x32_bf16 v[60:63], v[60:63], v[72:75], v[68:71]
	s_nop 2
	v_bitop3_b32 v68, v0, v1, 12 bitop3:0x36
	v_lshlrev_b32_e32 v119, 4, v68
	v_add_u32_e32 v127, v115, v119
	ds_read_b128 v[68:71], v127
	s_waitcnt lgkmcnt(1)
	v_mfma_f32_16x16x32_bf16 v[2:5], v[76:79], v[72:75], v[2:5]
	ds_read_b128 v[72:75], v127 offset:8192
	v_add_u32_e32 v101, 0x10000, v127
	v_add_u32_e32 v100, 0x12000, v127
	s_waitcnt vmcnt(0) lgkmcnt(1)
	v_mfma_f32_16x16x32_bf16 v[6:9], v[68:71], v[80:83], v[6:9]
	ds_read_b128 v[68:71], v127 offset:16384
	v_add_u32_e32 v99, 0x14000, v127
	v_add_u32_e32 v98, 0x16000, v127
	s_waitcnt lgkmcnt(1)
	v_mfma_f32_16x16x32_bf16 v[10:13], v[72:75], v[80:83], v[10:13]
	ds_read_b128 v[72:75], v127 offset:24576
	v_add_u32_e32 v97, 0x18000, v127
	v_add_u32_e32 v96, 0x1a000, v127
	s_waitcnt lgkmcnt(1)
	v_mfma_f32_16x16x32_bf16 v[18:21], v[68:71], v[80:83], v[18:21]
	v_add_u32_e32 v95, 0x1c000, v127
	v_add_u32_e32 v94, 0x1e000, v127
	s_waitcnt lgkmcnt(0)
	v_mfma_f32_16x16x32_bf16 v[14:17], v[72:75], v[80:83], v[14:17]
	ds_read_b128 v[68:71], v127 offset:32768
	ds_read_b128 v[72:75], v127 offset:40960
	s_waitcnt lgkmcnt(1)
	v_mfma_f32_16x16x32_bf16 v[26:29], v[68:71], v[80:83], v[26:29]
	global_load_dwordx4 v[68:71], v[58:59], off offset:256
	s_waitcnt lgkmcnt(0)
	v_mfma_f32_16x16x32_bf16 v[22:25], v[72:75], v[80:83], v[22:25]
	ds_read_b128 v[72:75], v127 offset:49152
	ds_read_b128 v[76:79], v127 offset:57344
	global_load_dwordx4 v[140:143], v[58:59], off offset:320
	s_waitcnt lgkmcnt(1)
	v_mfma_f32_16x16x32_bf16 v[30:33], v[72:75], v[80:83], v[30:33]
	ds_read_b128 v[72:75], v101
	s_waitcnt lgkmcnt(1)
	v_mfma_f32_16x16x32_bf16 v[38:41], v[76:79], v[80:83], v[38:41]
	ds_read_b128 v[76:79], v100
	s_waitcnt lgkmcnt(1)
	v_mfma_f32_16x16x32_bf16 v[34:37], v[72:75], v[80:83], v[34:37]
	ds_read_b128 v[72:75], v99
	s_waitcnt lgkmcnt(1)
	v_mfma_f32_16x16x32_bf16 v[46:49], v[76:79], v[80:83], v[46:49]
	ds_read_b128 v[76:79], v98
	s_waitcnt lgkmcnt(1)
	v_mfma_f32_16x16x32_bf16 v[42:45], v[72:75], v[80:83], v[42:45]
	ds_read_b128 v[72:75], v97
	s_waitcnt lgkmcnt(1)
	v_mfma_f32_16x16x32_bf16 v[54:57], v[76:79], v[80:83], v[54:57]
	ds_read_b128 v[76:79], v96
	s_waitcnt lgkmcnt(1)
	v_mfma_f32_16x16x32_bf16 v[50:53], v[72:75], v[80:83], v[50:53]
	ds_read_b128 v[72:75], v95
	s_waitcnt lgkmcnt(1)
	v_mfma_f32_16x16x32_bf16 v[64:67], v[76:79], v[80:83], v[64:67]
	ds_read_b128 v[76:79], v94
	s_waitcnt lgkmcnt(1)
	v_mfma_f32_16x16x32_bf16 v[60:63], v[72:75], v[80:83], v[60:63]
	v_bitop3_b32 v72, v0, v1, 16 bitop3:0x36
	v_lshlrev_b32_e32 v120, 4, v72
	v_add_u32_e32 v128, v115, v120
	ds_read_b128 v[72:75], v128
	s_waitcnt lgkmcnt(1)
	v_mfma_f32_16x16x32_bf16 v[2:5], v[76:79], v[80:83], v[2:5]
	ds_read_b128 v[76:79], v128 offset:8192
	v_add_u32_e32 v93, 0x10000, v128
	v_add_u32_e32 v92, 0x12000, v128
	s_waitcnt vmcnt(1) lgkmcnt(1)
	v_mfma_f32_16x16x32_bf16 v[6:9], v[72:75], v[68:71], v[6:9]
	ds_read_b128 v[72:75], v128 offset:16384
	v_add_u32_e32 v91, 0x14000, v128
	v_add_u32_e32 v90, 0x16000, v128
	s_waitcnt lgkmcnt(1)
	v_mfma_f32_16x16x32_bf16 v[10:13], v[76:79], v[68:71], v[10:13]
	ds_read_b128 v[76:79], v128 offset:24576
	v_add_u32_e32 v89, 0x18000, v128
	v_add_u32_e32 v88, 0x1a000, v128
	s_waitcnt lgkmcnt(1)
	v_mfma_f32_16x16x32_bf16 v[18:21], v[72:75], v[68:71], v[18:21]
	ds_read_b128 v[72:75], v128 offset:32768
	v_add_u32_e32 v87, 0x1c000, v128
	v_add_u32_e32 v86, 0x1e000, v128
	s_waitcnt lgkmcnt(1)
	v_mfma_f32_16x16x32_bf16 v[14:17], v[76:79], v[68:71], v[14:17]
	ds_read_b128 v[76:79], v128 offset:40960
	s_waitcnt lgkmcnt(1)
	v_mfma_f32_16x16x32_bf16 v[26:29], v[72:75], v[68:71], v[26:29]
	s_waitcnt lgkmcnt(0)
	v_mfma_f32_16x16x32_bf16 v[22:25], v[76:79], v[68:71], v[22:25]
	ds_read_b128 v[72:75], v128 offset:49152
	ds_read_b128 v[76:79], v128 offset:57344
	s_waitcnt lgkmcnt(1)
	v_mfma_f32_16x16x32_bf16 v[30:33], v[72:75], v[68:71], v[30:33]
	ds_read_b128 v[72:75], v93
	s_waitcnt lgkmcnt(1)
	v_mfma_f32_16x16x32_bf16 v[38:41], v[76:79], v[68:71], v[38:41]
	ds_read_b128 v[76:79], v92
	s_waitcnt lgkmcnt(1)
	v_mfma_f32_16x16x32_bf16 v[34:37], v[72:75], v[68:71], v[34:37]
	ds_read_b128 v[72:75], v91
	s_waitcnt lgkmcnt(1)
; #define LAS __attribute__((address_space(3)))
; template <class Sched> __device__ __forceinline__ void att_phase(LAS unsigned char* lds, const bf16_t* Kl, const bf16_t* Vl, const bf16_t* Qb, bf16_t* Ob, const Sched& S, int tid) {
;     ...
;             for (int s = 0; s < 8; ++s)
; #pragma unroll
;                 for (int kb = 0; kb < 16; ++kb) { const bf16x8_t af = *(const LAS bf16x8_t*)(fbase + kb * 8192 + (((4 * s + kg) ^ j) << 4));
;                     acc[kb] = __builtin_amdgcn_mfma_f32_16x16x32_bf16(af, qf[s], acc[kb], 0, 0, 0); }
	v_mfma_f32_16x16x32_bf16 v[46:49], v[76:79], v[68:71], v[46:49]
	ds_read_b128 v[76:79], v90
	s_waitcnt lgkmcnt(1)
	v_mfma_f32_16x16x32_bf16 v[42:45], v[72:75], v[68:71], v[42:45]
	ds_read_b128 v[72:75], v89
	s_waitcnt lgkmcnt(1)
	v_mfma_f32_16x16x32_bf16 v[54:57], v[76:79], v[68:71], v[54:57]
	ds_read_b128 v[76:79], v88
	s_waitcnt lgkmcnt(1)
	v_mfma_f32_16x16x32_bf16 v[50:53], v[72:75], v[68:71], v[50:53]
	ds_read_b128 v[72:75], v87
	s_waitcnt lgkmcnt(1)
	v_mfma_f32_16x16x32_bf16 v[64:67], v[76:79], v[68:71], v[64:67]
	ds_read_b128 v[76:79], v86
	s_waitcnt lgkmcnt(1)
	v_mfma_f32_16x16x32_bf16 v[60:63], v[72:75], v[68:71], v[60:63]
	v_bitop3_b32 v72, v0, v1, 20 bitop3:0x36
	v_lshlrev_b32_e32 v121, 4, v72
	v_add_u32_e32 v129, v115, v121
	ds_read_b128 v[72:75], v129
	s_waitcnt lgkmcnt(1)
	v_mfma_f32_16x16x32_bf16 v[2:5], v[76:79], v[68:71], v[2:5]
	ds_read_b128 v[68:71], v129 offset:8192
	v_add_u32_e32 v85, 0x10000, v129
	v_add_u32_e32 v84, 0x12000, v129
	s_waitcnt vmcnt(0) lgkmcnt(1)
	v_mfma_f32_16x16x32_bf16 v[6:9], v[72:75], v[140:143], v[6:9]
	ds_read_b128 v[72:75], v129 offset:16384
	v_add_u32_e32 v83, 0x14000, v129
	v_add_u32_e32 v82, 0x16000, v129
	s_waitcnt lgkmcnt(1)
	v_mfma_f32_16x16x32_bf16 v[10:13], v[68:71], v[140:143], v[10:13]
	ds_read_b128 v[68:71], v129 offset:24576
	v_add_u32_e32 v81, 0x18000, v129
	v_add_u32_e32 v80, 0x1a000, v129
	s_waitcnt lgkmcnt(1)
	v_mfma_f32_16x16x32_bf16 v[18:21], v[72:75], v[140:143], v[18:21]
	v_add_u32_e32 v79, 0x1c000, v129
	v_add_u32_e32 v78, 0x1e000, v129
	s_waitcnt lgkmcnt(0)
	v_mfma_f32_16x16x32_bf16 v[14:17], v[68:71], v[140:143], v[14:17]
	ds_read_b128 v[68:71], v129 offset:32768
	ds_read_b128 v[72:75], v129 offset:40960
	global_load_dwordx4 v[174:177], v[58:59], off offset:384
	s_waitcnt lgkmcnt(1)
	v_mfma_f32_16x16x32_bf16 v[26:29], v[68:71], v[140:143], v[26:29]
	s_waitcnt lgkmcnt(0)
	v_mfma_f32_16x16x32_bf16 v[22:25], v[72:75], v[140:143], v[22:25]
	ds_read_b128 v[68:71], v129 offset:49152
	ds_read_b128 v[72:75], v129 offset:57344
	global_load_dwordx4 v[178:181], v[58:59], off offset:448
	s_waitcnt lgkmcnt(1)
	v_mfma_f32_16x16x32_bf16 v[30:33], v[68:71], v[140:143], v[30:33]
	ds_read_b128 v[68:71], v85
	s_waitcnt lgkmcnt(1)
	v_mfma_f32_16x16x32_bf16 v[38:41], v[72:75], v[140:143], v[38:41]
	ds_read_b128 v[72:75], v84
	s_waitcnt lgkmcnt(1)
	v_mfma_f32_16x16x32_bf16 v[34:37], v[68:71], v[140:143], v[34:37]
	ds_read_b128 v[68:71], v83
	s_waitcnt lgkmcnt(1)
	v_mfma_f32_16x16x32_bf16 v[46:49], v[72:75], v[140:143], v[46:49]
	ds_read_b128 v[72:75], v82
	s_waitcnt lgkmcnt(1)
	v_mfma_f32_16x16x32_bf16 v[42:45], v[68:71], v[140:143], v[42:45]
	ds_read_b128 v[68:71], v81
	s_waitcnt lgkmcnt(1)
	v_mfma_f32_16x16x32_bf16 v[54:57], v[72:75], v[140:143], v[54:57]
	ds_read_b128 v[72:75], v80
	s_waitcnt lgkmcnt(1)
	v_mfma_f32_16x16x32_bf16 v[50:53], v[68:71], v[140:143], v[50:53]
	ds_read_b128 v[68:71], v79
	s_waitcnt lgkmcnt(1)
	v_mfma_f32_16x16x32_bf16 v[64:67], v[72:75], v[140:143], v[64:67]
	ds_read_b128 v[72:75], v78
	s_waitcnt lgkmcnt(1)
	v_mfma_f32_16x16x32_bf16 v[60:63], v[68:71], v[140:143], v[60:63]
	v_bitop3_b32 v68, v0, v1, 24 bitop3:0x36
	v_lshlrev_b32_e32 v122, 4, v68
	v_add_u32_e32 v139, v115, v122
	ds_read_b128 v[68:71], v139
	s_waitcnt lgkmcnt(1)
	v_mfma_f32_16x16x32_bf16 v[2:5], v[72:75], v[140:143], v[2:5]
	ds_read_b128 v[72:75], v139 offset:8192
	v_add_u32_e32 v77, 0x10000, v139
	v_add_u32_e32 v76, 0x12000, v139
	s_waitcnt vmcnt(1) lgkmcnt(1)
	v_mfma_f32_16x16x32_bf16 v[6:9], v[68:71], v[174:177], v[6:9]
	ds_read_b128 v[68:71], v139 offset:16384
	v_bitop3_b32 v1, v0, v1, 28 bitop3:0x36
	v_lshlrev_b32_e32 v123, 4, v1
	s_waitcnt lgkmcnt(1)
	v_mfma_f32_16x16x32_bf16 v[10:13], v[72:75], v[174:177], v[10:13]
	ds_read_b128 v[72:75], v139 offset:24576
	v_xor_b32_e32 v1, 16, v230
	s_waitcnt lgkmcnt(1)
	v_mfma_f32_16x16x32_bf16 v[18:21], v[68:71], v[174:177], v[18:21]
	ds_read_b128 v[68:71], v139 offset:32768
	s_waitcnt lgkmcnt(1)
	v_mfma_f32_16x16x32_bf16 v[14:17], v[72:75], v[174:177], v[14:17]
	ds_read_b128 v[72:75], v139 offset:40960
	s_waitcnt lgkmcnt(1)
	v_mfma_f32_16x16x32_bf16 v[26:29], v[68:71], v[174:177], v[26:29]
	s_waitcnt lgkmcnt(0)
	v_mfma_f32_16x16x32_bf16 v[22:25], v[72:75], v[174:177], v[22:25]
	ds_read_b128 v[68:71], v139 offset:49152
	ds_read_b128 v[72:75], v139 offset:57344
	ds_read_b128 v[140:143], v76
	s_waitcnt lgkmcnt(2)
	v_mfma_f32_16x16x32_bf16 v[30:33], v[68:71], v[174:177], v[30:33]
	ds_read_b128 v[68:71], v77
	s_waitcnt lgkmcnt(2)
	v_mfma_f32_16x16x32_bf16 v[38:41], v[72:75], v[174:177], v[38:41]
	v_add_u32_e32 v75, 0x14000, v139
	v_add_u32_e32 v74, 0x16000, v139
	v_add_u32_e32 v73, 0x18000, v139
	s_waitcnt lgkmcnt(0)
	v_mfma_f32_16x16x32_bf16 v[34:37], v[68:71], v[174:177], v[34:37]
	ds_read_b128 v[68:71], v75
	v_add_u32_e32 v72, 0x1a000, v139
	v_mfma_f32_16x16x32_bf16 v[182:185], v[140:143], v[174:177], v[46:49]
	v_add_u32_e32 v141, v115, v123
	s_nop 1
	ds_read_b128 v[46:49], v74
	s_waitcnt lgkmcnt(1)
	v_mfma_f32_16x16x32_bf16 v[42:45], v[68:71], v[174:177], v[42:45]
	ds_read_b128 v[68:71], v73
	s_waitcnt lgkmcnt(1)
	v_mfma_f32_16x16x32_bf16 v[186:189], v[46:49], v[174:177], v[54:57]
	ds_read_b128 v[46:49], v72
	s_waitcnt lgkmcnt(1)
	v_mfma_f32_16x16x32_bf16 v[190:193], v[68:71], v[174:177], v[50:53]
	v_add_u32_e32 v71, 0x1c000, v139
	v_add_u32_e32 v70, 0x1e000, v139
	v_add_u32_e32 v69, 0x10000, v141
	ds_read_b128 v[50:53], v71
	s_waitcnt lgkmcnt(1)
	v_mfma_f32_16x16x32_bf16 v[194:197], v[46:49], v[174:177], v[64:67]
	ds_read_b128 v[46:49], v70
	v_add_u32_e32 v68, 0x12000, v141
	s_nop 0
	v_add_u32_e32 v67, 0x14000, v141
	s_waitcnt lgkmcnt(1)
; #define LAS __attribute__((address_space(3)))
; template <class Sched> __device__ __forceinline__ void att_phase(LAS unsigned char* lds, const bf16_t* Kl, const bf16_t* Vl, const bf16_t* Qb, bf16_t* Ob, const Sched& S, int tid) {
;     ...
;             for (int s = 0; s < 8; ++s)
; #pragma unroll
;                 for (int kb = 0; kb < 16; ++kb) { const bf16x8_t af = *(const LAS bf16x8_t*)(fbase + kb * 8192 + (((4 * s + kg) ^ j) << 4));
;                     acc[kb] = __builtin_amdgcn_mfma_f32_16x16x32_bf16(af, qf[s], acc[kb], 0, 0, 0); }
;             float mx = acc[0][0];
; #pragma unroll
;             for (int kb = 0; kb < 16; ++kb) mx = fmaxf(fmaxf(mx, fmaxf(acc[kb][0], acc[kb][1])), fmaxf(acc[kb][2], acc[kb][3]));
;             mx = fmaxf(mx, __shfl_xor(mx, 16)); mx = fmaxf(mx, __shfl_xor(mx, 32));
	v_mfma_f32_16x16x32_bf16 v[198:201], v[50:53], v[174:177], v[60:63]
	ds_read_b128 v[50:53], v141
	v_add_u32_e32 v66, 0x16000, v141
	v_add_u32_e32 v65, 0x18000, v141
	s_waitcnt lgkmcnt(1)
	v_mfma_f32_16x16x32_bf16 v[2:5], v[46:49], v[174:177], v[2:5]
	ds_read_b128 v[46:49], v141 offset:8192
	v_add_u32_e32 v64, 0x1a000, v141
	v_add_u32_e32 v63, 0x1c000, v141
	s_waitcnt vmcnt(0) lgkmcnt(1)
	v_mfma_f32_16x16x32_bf16 v[174:177], v[50:53], v[178:181], v[6:9]
	v_add_u32_e32 v62, 0x1e000, v141
	s_nop 1
	ds_read_b128 v[6:9], v141 offset:16384
	s_waitcnt lgkmcnt(1)
	v_mfma_f32_16x16x32_bf16 v[202:205], v[46:49], v[178:181], v[10:13]
	s_nop 2
	ds_read_b128 v[10:13], v141 offset:24576
	s_waitcnt lgkmcnt(1)
	v_mfma_f32_16x16x32_bf16 v[206:209], v[6:9], v[178:181], v[18:21]
	ds_read_b128 v[6:9], v141 offset:32768
	s_waitcnt lgkmcnt(1)
	v_mfma_f32_16x16x32_bf16 v[210:213], v[10:13], v[178:181], v[14:17]
	ds_read_b128 v[10:13], v141 offset:40960
	s_waitcnt lgkmcnt(1)
	v_mfma_f32_16x16x32_bf16 v[54:57], v[6:9], v[178:181], v[26:29]
	v_and_b32_e32 v6, 64, v230
	v_add_u32_e32 v6, 64, v6
	v_cmp_lt_i32_e32 vcc, v1, v6
	s_waitcnt lgkmcnt(0)
	v_mfma_f32_16x16x32_bf16 v[8:11], v[10:13], v[178:181], v[22:25]
	ds_read_b128 v[12:15], v141 offset:49152
	ds_read_b128 v[16:19], v141 offset:57344
	s_nop 0
	ds_read_b128 v[22:25], v67
	ds_read_b128 v[26:29], v66
	s_waitcnt lgkmcnt(3)
	v_mfma_f32_16x16x32_bf16 v[46:49], v[12:15], v[178:181], v[30:33]
	ds_read_b128 v[12:15], v69
	v_cndmask_b32_e32 v1, v230, v1, vcc
	v_lshlrev_b32_e32 v142, 2, v1
	s_waitcnt lgkmcnt(3)
	v_mfma_f32_16x16x32_bf16 v[50:53], v[16:19], v[178:181], v[38:41]
	ds_read_b128 v[18:21], v68
	v_max_f32_e32 v1, v177, v177
	s_waitcnt lgkmcnt(3)
	v_mfma_f32_16x16x32_bf16 v[38:41], v[22:25], v[178:181], v[42:45]
	ds_read_b128 v[22:25], v65
	s_waitcnt lgkmcnt(1)
	v_mfma_f32_16x16x32_bf16 v[18:21], v[18:21], v[178:181], v[182:185]
	s_nop 2
	ds_read_b128 v[182:185], v62
	v_mfma_f32_16x16x32_bf16 v[42:45], v[26:29], v[178:181], v[186:189]
	ds_read_b128 v[26:29], v64
	s_waitcnt lgkmcnt(2)
	v_mfma_f32_16x16x32_bf16 v[30:33], v[22:25], v[178:181], v[190:193]
	ds_read_b128 v[22:25], v63
	v_mfma_f32_16x16x32_bf16 v[14:17], v[12:15], v[178:181], v[34:37]
	s_waitcnt lgkmcnt(1)
	v_mfma_f32_16x16x32_bf16 v[34:37], v[26:29], v[178:181], v[194:197]
	v_mfma_f32_16x16x32_bf16 v[26:29], v[182:185], v[178:181], v[2:5]
	s_nop 2
	v_max_f32_e32 v2, v176, v176
	v_max_f32_e32 v1, v2, v1
	v_max_f32_e32 v2, v203, v203
	v_max_f32_e32 v3, v202, v202
	v_max_f32_e32 v2, v3, v2
	v_max_f32_e32 v3, v205, v205
	v_max_f32_e32 v4, v204, v204
	v_max3_f32 v1, v174, v175, v1
	v_max_f32_e32 v3, v4, v3
	v_max3_f32 v1, v1, v2, v3
	v_max_f32_e32 v2, v207, v207
	v_max_f32_e32 v3, v206, v206
	v_max_f32_e32 v2, v3, v2
	v_max_f32_e32 v3, v209, v209
	v_max_f32_e32 v4, v208, v208
	v_max_f32_e32 v3, v4, v3
	v_max3_f32 v1, v1, v2, v3
	v_max_f32_e32 v2, v211, v211
	v_max_f32_e32 v3, v210, v210
	v_max_f32_e32 v2, v3, v2
	v_max_f32_e32 v3, v213, v213
	v_max_f32_e32 v4, v212, v212
	v_max_f32_e32 v3, v4, v3
	v_max3_f32 v1, v1, v2, v3
	v_max_f32_e32 v2, v55, v55
	v_max_f32_e32 v3, v54, v54
	v_max_f32_e32 v2, v3, v2
	v_max_f32_e32 v3, v57, v57
	v_max_f32_e32 v4, v56, v56
	v_max_f32_e32 v3, v4, v3
	v_max3_f32 v1, v1, v2, v3
	v_max_f32_e32 v2, v9, v9
	v_max_f32_e32 v3, v8, v8
	v_max_f32_e32 v2, v3, v2
	v_max_f32_e32 v3, v11, v11
	v_max_f32_e32 v4, v10, v10
	v_max_f32_e32 v3, v4, v3
	v_max3_f32 v1, v1, v2, v3
	v_max_f32_e32 v2, v47, v47
	v_max_f32_e32 v3, v46, v46
	v_max_f32_e32 v2, v3, v2
	v_max_f32_e32 v3, v49, v49
	v_max_f32_e32 v4, v48, v48
	v_max_f32_e32 v3, v4, v3
	v_max3_f32 v1, v1, v2, v3
	v_max_f32_e32 v2, v51, v51
	v_max_f32_e32 v3, v50, v50
	v_max_f32_e32 v2, v3, v2
	v_max_f32_e32 v3, v53, v53
	v_max_f32_e32 v4, v52, v52
	v_max_f32_e32 v3, v4, v3
	v_max3_f32 v1, v1, v2, v3
	v_max_f32_e32 v2, v15, v15
	v_max_f32_e32 v3, v14, v14
	v_max_f32_e32 v2, v3, v2
	v_max_f32_e32 v3, v17, v17
	v_max_f32_e32 v4, v16, v16
	v_max_f32_e32 v3, v4, v3
	v_max3_f32 v1, v1, v2, v3
	v_max_f32_e32 v2, v19, v19
	v_max_f32_e32 v3, v18, v18
	v_max_f32_e32 v2, v3, v2
	v_max_f32_e32 v3, v21, v21
	v_max_f32_e32 v4, v20, v20
	v_max_f32_e32 v3, v4, v3
	v_max3_f32 v1, v1, v2, v3
	v_max_f32_e32 v2, v39, v39
	v_max_f32_e32 v3, v38, v38
	v_max_f32_e32 v2, v3, v2
	v_max_f32_e32 v3, v41, v41
	v_max_f32_e32 v4, v40, v40
	v_max_f32_e32 v3, v4, v3
	v_max3_f32 v1, v1, v2, v3
	v_max_f32_e32 v2, v43, v43
	v_max_f32_e32 v3, v42, v42
	v_max_f32_e32 v2, v3, v2
	v_max_f32_e32 v3, v45, v45
	v_max_f32_e32 v4, v44, v44
	v_max_f32_e32 v3, v4, v3
	v_max3_f32 v1, v1, v2, v3
	v_max_f32_e32 v2, v31, v31
	v_max_f32_e32 v3, v30, v30
	v_max_f32_e32 v2, v3, v2
	v_max_f32_e32 v3, v33, v33
	v_max_f32_e32 v4, v32, v32
	s_waitcnt lgkmcnt(0)
	v_mfma_f32_16x16x32_bf16 v[22:25], v[22:25], v[178:181], v[198:201]
	v_max_f32_e32 v3, v4, v3
	v_max3_f32 v1, v1, v2, v3
	v_max_f32_e32 v2, v35, v35
	v_max_f32_e32 v3, v34, v34
	v_max_f32_e32 v2, v3, v2
	v_max_f32_e32 v3, v37, v37
	v_max_f32_e32 v4, v36, v36
	v_max_f32_e32 v3, v4, v3
	v_max3_f32 v1, v1, v2, v3
	v_max_f32_e32 v2, v23, v23
	v_max_f32_e32 v3, v22, v22
	v_max_f32_e32 v2, v3, v2
	v_max_f32_e32 v3, v25, v25
	v_max_f32_e32 v4, v24, v24
	v_max_f32_e32 v3, v4, v3
	v_max3_f32 v1, v1, v2, v3
	v_max_f32_e32 v2, v27, v27
	v_max_f32_e32 v3, v26, v26
	v_max_f32_e32 v2, v3, v2
	v_max_f32_e32 v3, v29, v29
	v_max_f32_e32 v4, v28, v28
	v_max_f32_e32 v3, v4, v3
	v_max3_f32 v1, v1, v2, v3
	ds_bpermute_b32 v2, v142, v1
	v_xor_b32_e32 v3, 32, v230
	v_cmp_lt_i32_e32 vcc, v3, v6
	s_waitcnt lgkmcnt(0)
; __device__ __forceinline__ unsigned cvtpk(float lo, float hi) { unsigned r; asm volatile("v_cvt_pk_bf16_f32 %0, %1, %2" : "=v"(r) : "v"(lo), "v"(hi)); return r; }
; template <class Sched> __device__ __forceinline__ void att_phase(LAS unsigned char* lds, const bf16_t* Kl, const bf16_t* Vl, const bf16_t* Qb, bf16_t* Ob, const Sched& S, int tid) {
;     ...
;             mx = fmaxf(mx, __shfl_xor(mx, 16)); mx = fmaxf(mx, __shfl_xor(mx, 32));
;             const float mxc = mx * cs; float sum = 0.f;
; #pragma unroll
;             for (int t = 0; t < 8; ++t) { f32x4 p0, p1;
; #pragma unroll
;                 for (int e = 0; e < 4; ++e) { p0[e] = __builtin_amdgcn_exp2f(acc[2 * t][e] * cs - mxc); p1[e] = __builtin_amdgcn_exp2f(acc[2 * t + 1][e] * cs - mxc); }
;                 sum += (p0[0] + p0[1]) + (p0[2] + p0[3]) + (p1[0] + p1[1]) + (p1[2] + p1[3]);
;                 u32x4 w; w.x = cvtpk(p0[0], p0[1]); w.y = cvtpk(p0[2], p0[3]); w.z = cvtpk(p1[0], p1[1]); w.w = cvtpk(p1[2], p1[3]); pf[hf][t] = __builtin_bit_cast(bf16x8_t, w); }
	v_max_f32_e32 v2, v2, v2
	v_cndmask_b32_e32 v3, v230, v3, vcc
	v_lshlrev_b32_e32 v143, 2, v3
	v_max_f32_e32 v1, v1, v2
	ds_bpermute_b32 v2, v143, v1
	s_waitcnt lgkmcnt(0)
	v_max_f32_e32 v0, v2, v2
	v_max_f32_e32 v1, v1, v0
	v_mov_b32_e32 v0, v28
	v_pk_mul_f32 v[60:61], v[0:1], s[80:81] op_sel_hi:[1,0]
	s_nop 0
	v_fma_f32 v0, v174, s80, -v61
	v_exp_f32_e32 v5, v0
	v_fma_f32 v0, v202, s80, -v61
	v_exp_f32_e32 v7, v0
	v_fma_f32 v0, v175, s80, -v61
	v_exp_f32_e32 v13, v0
	v_fma_f32 v0, v203, s80, -v61
	v_exp_f32_e32 v163, v0
	v_fma_f32 v0, v176, s80, -v61
	v_exp_f32_e32 v175, v0
	v_fma_f32 v0, v204, s80, -v61
	v_exp_f32_e32 v179, v0
	v_fma_f32 v0, v177, s80, -v61
	v_exp_f32_e32 v177, v0
	v_fma_f32 v0, v205, s80, -v61
	v_exp_f32_e32 v181, v0
	v_fma_f32 v0, v206, s80, -v61
	v_exp_f32_e32 v4, v0
	v_fma_f32 v0, v210, s80, -v61
	v_exp_f32_e32 v6, v0
	v_fma_f32 v0, v207, s80, -v61
	v_exp_f32_e32 v12, v0
	v_fma_f32 v0, v211, s80, -v61
	v_exp_f32_e32 v162, v0
	v_fma_f32 v0, v208, s80, -v61
	v_exp_f32_e32 v174, v0
	v_fma_f32 v0, v212, s80, -v61
	v_exp_f32_e32 v178, v0
	v_fma_f32 v0, v209, s80, -v61
	v_exp_f32_e32 v176, v0
	v_fma_f32 v0, v213, s80, -v61
	v_exp_f32_e32 v180, v0
	v_pk_add_f32 v[0:1], v[4:5], v[12:13]
	v_pk_add_f32 v[2:3], v[174:175], v[176:177]
	v_fma_f32 v14, v14, s80, -v61
	v_pk_add_f32 v[0:1], v[0:1], v[2:3]
	v_pk_add_f32 v[2:3], v[6:7], v[162:163]
	s_nop 0
	v_pk_add_f32 v[0:1], v[2:3], v[0:1]
	v_pk_add_f32 v[2:3], v[178:179], v[180:181]
	s_nop 0
	v_pk_add_f32 v[182:183], v[2:3], v[0:1]
	v_cvt_pk_bf16_f32 v0, v5, v13
	v_cvt_pk_bf16_f32 v1, v175, v177
	v_cvt_pk_bf16_f32 v2, v7, v163
	v_fma_f32 v7, v54, s80, -v61
	v_cvt_pk_bf16_f32 v3, v179, v181
	v_cvt_pk_bf16_f32 v4, v4, v12
	v_exp_f32_e32 v12, v7
	v_fma_f32 v7, v8, s80, -v61
	v_exp_f32_e32 v175, v7
	v_fma_f32 v7, v55, s80, -v61
	v_exp_f32_e32 v8, v7
	v_fma_f32 v7, v9, s80, -v61
	v_exp_f32_e32 v55, v7
	v_fma_f32 v7, v56, s80, -v61
	v_exp_f32_e32 v13, v7
	v_fma_f32 v7, v10, s80, -v61
	v_cvt_pk_bf16_f32 v5, v174, v176
	v_exp_f32_e32 v174, v7
	v_fma_f32 v7, v57, s80, -v61
	v_exp_f32_e32 v9, v7
	v_fma_f32 v7, v11, s80, -v61
	v_exp_f32_e32 v54, v7
	v_add_f32_e32 v28, 0, v183
	v_pk_add_f32 v[10:11], v[12:13], v[8:9]
	v_add_f32_e32 v163, v182, v28
	v_pk_add_f32 v[10:11], v[10:11], v[10:11] op_sel:[0,1] op_sel_hi:[1,0]
	v_pk_add_f32 v[56:57], v[174:175], v[54:55]
	v_cvt_pk_bf16_f32 v6, v6, v162
	v_cvt_pk_bf16_f32 v7, v178, v180
	v_cvt_pk_bf16_f32 v8, v12, v8
	v_cvt_pk_bf16_f32 v9, v13, v9
	v_fma_f32 v12, v46, s80, -v61
	v_pk_add_f32 v[10:11], v[56:57], v[10:11] op_sel:[1,0] op_sel_hi:[0,1]
	v_fma_f32 v13, v50, s80, -v61
	v_fma_f32 v28, v51, s80, -v61
	v_fma_f32 v46, v52, s80, -v61
	v_pk_add_f32 v[56:57], v[56:57], v[10:11]
	v_cvt_pk_bf16_f32 v10, v175, v55
	v_exp_f32_e32 v55, v13
	v_fma_f32 v13, v47, s80, -v61
	v_exp_f32_e32 v47, v28
	v_fma_f32 v28, v48, s80, -v61
	v_exp_f32_e32 v51, v46
	v_fma_f32 v46, v49, s80, -v61
	v_exp_f32_e32 v12, v12
	v_exp_f32_e32 v13, v13
	v_exp_f32_e32 v28, v28
	v_exp_f32_e32 v46, v46
	v_cvt_pk_bf16_f32 v11, v174, v54
	v_exp_f32_e32 v54, v14
	v_fma_f32 v14, v18, s80, -v61
	v_exp_f32_e32 v50, v14
	v_fma_f32 v14, v15, s80, -v61
	v_fma_f32 v48, v53, s80, -v61
	v_add_f32_e32 v53, v12, v13
	v_add_f32_e32 v175, v28, v46
	v_cvt_pk_bf16_f32 v12, v12, v13
	v_cvt_pk_bf16_f32 v13, v28, v46
	v_exp_f32_e32 v46, v14
	v_fma_f32 v14, v19, s80, -v61
	v_exp_f32_e32 v49, v48
	v_exp_f32_e32 v48, v14
	v_fma_f32 v14, v16, s80, -v61
	v_exp_f32_e32 v52, v14
	v_fma_f32 v14, v20, s80, -v61
	v_exp_f32_e32 v20, v14
	v_fma_f32 v14, v17, s80, -v61
	v_exp_f32_e32 v174, v14
	v_fma_f32 v14, v21, s80, -v61
	v_exp_f32_e32 v162, v14
	v_pk_add_f32 v[16:17], v[54:55], v[46:47]
	v_pk_add_f32 v[18:19], v[52:53], v[174:175]
	v_mov_b32_e32 v21, v56
	v_pk_add_f32 v[16:17], v[16:17], v[18:19]
	v_pk_add_f32 v[18:19], v[50:51], v[48:49]
	v_cvt_pk_bf16_f32 v14, v55, v47
	v_cvt_pk_bf16_f32 v15, v51, v49
	s_nop 0
	v_pk_add_f32 v[16:17], v[18:19], v[16:17]
	v_pk_add_f32 v[18:19], v[20:21], v[162:163]
	s_nop 0
	v_pk_add_f32 v[16:17], v[16:17], v[18:19]
	v_fma_f32 v19, v38, s80, -v61
	v_exp_f32_e32 v38, v19
	v_fma_f32 v19, v42, s80, -v61
	v_exp_f32_e32 v47, v19
	v_fma_f32 v19, v39, s80, -v61
	v_exp_f32_e32 v42, v19
	v_fma_f32 v19, v43, s80, -v61
	v_exp_f32_e32 v49, v19
	v_fma_f32 v19, v40, s80, -v61
	v_exp_f32_e32 v39, v19
	v_fma_f32 v19, v44, s80, -v61
	v_pk_add_f32 v[56:57], v[16:17], v[16:17] op_sel_hi:[0,1]
	v_cvt_pk_bf16_f32 v16, v54, v46
	v_exp_f32_e32 v46, v19
	v_fma_f32 v19, v41, s80, -v61
	v_exp_f32_e32 v43, v19
	v_fma_f32 v19, v45, s80, -v61
	v_cvt_pk_bf16_f32 v17, v52, v174
	v_cvt_pk_bf16_f32 v18, v50, v48
	v_exp_f32_e32 v48, v19
	v_cvt_pk_bf16_f32 v19, v20, v162
	v_pk_add_f32 v[20:21], v[38:39], v[42:43]
	v_pk_add_f32 v[40:41], v[46:47], v[48:49]
	v_pk_add_f32 v[20:21], v[20:21], v[20:21] op_sel:[0,1] op_sel_hi:[1,0]
	s_nop 0
	v_pk_add_f32 v[20:21], v[40:41], v[20:21] op_sel:[1,0] op_sel_hi:[0,1]
	v_pk_add_f32 v[40:41], v[40:41], v[20:21]
	v_fma_f32 v21, v30, s80, -v61
	v_exp_f32_e32 v28, v21
	v_fma_f32 v21, v34, s80, -v61
	v_exp_f32_e32 v45, v21
	v_fma_f32 v21, v31, s80, -v61
	v_cvt_pk_bf16_f32 v20, v38, v42
	v_exp_f32_e32 v38, v21
	v_fma_f32 v21, v35, s80, -v61
	v_exp_f32_e32 v31, v21
	v_fma_f32 v21, v32, s80, -v61
	v_exp_f32_e32 v41, v21
	v_fma_f32 v21, v36, s80, -v61
	v_exp_f32_e32 v35, v21
	v_fma_f32 v21, v33, s80, -v61
	v_exp_f32_e32 v42, v21
	v_fma_f32 v21, v37, s80, -v61
	v_exp_f32_e32 v33, v21
	v_fma_f32 v21, v22, s80, -v61
	v_exp_f32_e32 v44, v21
	v_fma_f32 v21, v26, s80, -v61
	v_exp_f32_e32 v34, v21
	v_fma_f32 v21, v23, s80, -v61
	v_exp_f32_e32 v30, v21
	v_fma_f32 v21, v27, s80, -v61
	v_exp_f32_e32 v32, v21
	v_fma_f32 v21, v24, s80, -v61
	v_exp_f32_e32 v36, v21
	v_sub_f32_e32 v21, v60, v61
	v_exp_f32_e32 v52, v21
	v_fma_f32 v21, v25, s80, -v61
	v_exp_f32_e32 v50, v21
	v_fma_f32 v21, v29, s80, -v61
	v_exp_f32_e32 v56, v21
	v_add_f32_e32 v37, v28, v38
	v_add_f32_e32 v51, v41, v42
	v_pk_add_f32 v[22:23], v[44:45], v[30:31]
	v_pk_add_f32 v[24:25], v[36:37], v[50:51]
	v_mov_b32_e32 v53, v40
	v_pk_add_f32 v[22:23], v[22:23], v[24:25]
	v_pk_add_f32 v[24:25], v[34:35], v[32:33]
	v_cvt_pk_bf16_f32 v21, v39, v43
	s_nop 0
	v_pk_add_f32 v[22:23], v[24:25], v[22:23]
	v_pk_add_f32 v[24:25], v[52:53], v[56:57]
	s_nop 0
	v_pk_add_f32 v[22:23], v[22:23], v[24:25]
	s_nop 0
	v_add_f32_e32 v25, v22, v23
	ds_bpermute_b32 v26, v142, v25
	v_cvt_pk_bf16_f32 v22, v47, v49
	v_cvt_pk_bf16_f32 v23, v46, v48
	v_cvt_pk_bf16_f32 v24, v28, v38
	s_waitcnt lgkmcnt(0)
; #define LAS __attribute__((address_space(3)))
; __device__ __forceinline__ unsigned cvtpk(float lo, float hi) { unsigned r; asm volatile("v_cvt_pk_bf16_f32 %0, %1, %2" : "=v"(r) : "v"(lo), "v"(hi)); return r; }
; template <class Sched> __device__ __forceinline__ void att_phase(LAS unsigned char* lds, const bf16_t* Kl, const bf16_t* Vl, const bf16_t* Qb, bf16_t* Ob, const Sched& S, int tid) {
;     ...
;         for (int hf = 0; hf < 2; ++hf) {
;             bf16x8_t qf[8];
; #pragma unroll
;             for (int s = 0; s < 8; ++s) qf[s] = *(const bf16x8_t*)(qrow + (size_t)hf * 128 * 1024 + 32 * s + 8 * kg);
;             f32x4 acc[16];
; #pragma unroll
;             for (int kb = 0; kb < 16; ++kb) acc[kb] = (f32x4){0.f, 0.f, 0.f, 0.f};
; #pragma unroll
;             for (int s = 0; s < 8; ++s)
; #pragma unroll
;                 for (int kb = 0; kb < 16; ++kb) { const bf16x8_t af = *(const LAS bf16x8_t*)(fbase + kb * 8192 + (((4 * s + kg) ^ j) << 4));
;                     acc[kb] = __builtin_amdgcn_mfma_f32_16x16x32_bf16(af, qf[s], acc[kb], 0, 0, 0); }
;             float mx = acc[0][0];
; #pragma unroll
;             for (int kb = 0; kb < 16; ++kb) mx = fmaxf(fmaxf(mx, fmaxf(acc[kb][0], acc[kb][1])), fmaxf(acc[kb][2], acc[kb][3]));
;             mx = fmaxf(mx, __shfl_xor(mx, 16)); mx = fmaxf(mx, __shfl_xor(mx, 32));
;             const float mxc = mx * cs; float sum = 0.f;
; #pragma unroll
;             for (int t = 0; t < 8; ++t) { f32x4 p0, p1;
; #pragma unroll
;                 for (int e = 0; e < 4; ++e) { p0[e] = __builtin_amdgcn_exp2f(acc[2 * t][e] * cs - mxc); p1[e] = __builtin_amdgcn_exp2f(acc[2 * t + 1][e] * cs - mxc); }
;                 sum += (p0[0] + p0[1]) + (p0[2] + p0[3]) + (p1[0] + p1[1]) + (p1[2] + p1[3]);
;                 u32x4 w; w.x = cvtpk(p0[0], p0[1]); w.y = cvtpk(p0[2], p0[3]); w.z = cvtpk(p1[0], p1[1]); w.w = cvtpk(p1[2], p1[3]); pf[hf][t] = __builtin_bit_cast(bf16x8_t, w); }
;             sum += __shfl_xor(sum, 16); sum += __shfl_xor(sum, 32);
;             inv[hf] = 1.f / sum;
	v_add_f32_e32 v29, v25, v26
	ds_bpermute_b32 v37, v143, v29
	v_cvt_pk_bf16_f32 v25, v41, v42
	v_cvt_pk_bf16_f32 v26, v45, v31
	v_cvt_pk_bf16_f32 v27, v35, v33
	v_cvt_pk_bf16_f32 v28, v44, v30
	s_waitcnt lgkmcnt(0)
	v_add_f32_e32 v33, v29, v37
	v_div_scale_f32 v35, s[6:7], v33, v33, 1.0
	v_rcp_f32_e32 v37, v35
	v_cvt_pk_bf16_f32 v29, v36, v50
	v_cvt_pk_bf16_f32 v30, v34, v32
	v_cvt_pk_bf16_f32 v31, v52, v56
	s_nop 0
	v_fma_f32 v32, -v35, v37, 1.0
	v_fmac_f32_e32 v37, v32, v37
	v_div_scale_f32 v32, vcc, 1.0, v33, 1.0
	v_mul_f32_e32 v34, v32, v37
	v_fma_f32 v36, -v35, v34, v32
	v_fmac_f32_e32 v34, v36, v37
	v_fma_f32 v32, -v35, v34, v32
	v_div_fmas_f32 v32, v32, v37, v34
	v_div_fixup_f32 v140, v32, v33, 1.0
	v_add_co_u32_e32 v32, vcc, s15, v58
	s_nop 1
	v_addc_co_u32_e32 v33, vcc, 0, v59, vcc
	global_load_dwordx4 v[174:177], v[32:33], off
	global_load_dwordx4 v[56:59], v[32:33], off offset:64
	global_load_dwordx4 v[52:55], v[32:33], off offset:128
	global_load_dwordx4 v[48:51], v[32:33], off offset:192
	global_load_dwordx4 v[44:47], v[32:33], off offset:256
	global_load_dwordx4 v[40:43], v[32:33], off offset:320
	global_load_dwordx4 v[36:39], v[32:33], off offset:384
	s_nop 0
	global_load_dwordx4 v[32:35], v[32:33], off offset:448
	ds_read_b128 v[178:181], v124
	ds_read_b128 v[182:185], v124 offset:8192
	ds_read_b128 v[186:189], v124 offset:16384
	ds_read_b128 v[190:193], v124 offset:24576
	ds_read_b128 v[194:197], v124 offset:32768
	ds_read_b128 v[198:201], v124 offset:40960
	ds_read_b128 v[202:205], v124 offset:49152
	ds_read_b128 v[206:209], v124 offset:57344
	ds_read_b128 v[210:213], v161
	ds_read_b128 v[214:217], v159
	ds_read_b128 v[160:163], v160
	ds_read_b128 v[218:221], v158
	ds_read_b128 v[246:249], v157
	ds_read_b128 v[156:159], v156
	ds_read_b128 v[234:237], v155
	ds_read_b128 v[238:241], v154
	s_waitcnt vmcnt(7) lgkmcnt(14)
	v_mfma_f32_16x16x32_bf16 v[178:181], v[178:181], v[174:177], 0
	v_mfma_f32_16x16x32_bf16 v[182:185], v[182:185], v[174:177], 0
	s_waitcnt lgkmcnt(13)
	v_mfma_f32_16x16x32_bf16 v[186:189], v[186:189], v[174:177], 0
	s_waitcnt lgkmcnt(12)
	v_mfma_f32_16x16x32_bf16 v[190:193], v[190:193], v[174:177], 0
	s_waitcnt lgkmcnt(11)
	v_mfma_f32_16x16x32_bf16 v[194:197], v[194:197], v[174:177], 0
	s_waitcnt lgkmcnt(10)
	v_mfma_f32_16x16x32_bf16 v[198:201], v[198:201], v[174:177], 0
	s_waitcnt lgkmcnt(9)
	v_mfma_f32_16x16x32_bf16 v[202:205], v[202:205], v[174:177], 0
	s_waitcnt lgkmcnt(8)
	v_mfma_f32_16x16x32_bf16 v[206:209], v[206:209], v[174:177], 0
	s_waitcnt lgkmcnt(7)
	v_mfma_f32_16x16x32_bf16 v[210:213], v[210:213], v[174:177], 0
	s_waitcnt lgkmcnt(5)
	v_mfma_f32_16x16x32_bf16 v[160:163], v[160:163], v[174:177], 0
	v_mfma_f32_16x16x32_bf16 v[214:217], v[214:217], v[174:177], 0
	s_waitcnt lgkmcnt(4)
	v_mfma_f32_16x16x32_bf16 v[218:221], v[218:221], v[174:177], 0
	s_waitcnt lgkmcnt(3)
	v_mfma_f32_16x16x32_bf16 v[246:249], v[246:249], v[174:177], 0
	s_waitcnt lgkmcnt(2)
	v_mfma_f32_16x16x32_bf16 v[156:159], v[156:159], v[174:177], 0
	s_waitcnt lgkmcnt(1)
	v_mfma_f32_16x16x32_bf16 v[234:237], v[234:237], v[174:177], 0
	s_waitcnt lgkmcnt(0)
	v_mfma_f32_16x16x32_bf16 v[174:177], v[238:241], v[174:177], 0
	ds_read_b128 v[238:241], v125
	s_waitcnt vmcnt(6) lgkmcnt(0)
	v_mfma_f32_16x16x32_bf16 v[178:181], v[238:241], v[56:59], v[178:181]
	ds_read_b128 v[238:241], v125 offset:8192
	s_waitcnt lgkmcnt(0)
	v_mfma_f32_16x16x32_bf16 v[182:185], v[238:241], v[56:59], v[182:185]
	ds_read_b128 v[238:241], v125 offset:16384
	s_waitcnt lgkmcnt(0)
	v_mfma_f32_16x16x32_bf16 v[186:189], v[238:241], v[56:59], v[186:189]
	ds_read_b128 v[238:241], v125 offset:24576
	s_waitcnt lgkmcnt(0)
	v_mfma_f32_16x16x32_bf16 v[190:193], v[238:241], v[56:59], v[190:193]
	ds_read_b128 v[238:241], v125 offset:32768
	s_waitcnt lgkmcnt(0)
	v_mfma_f32_16x16x32_bf16 v[194:197], v[238:241], v[56:59], v[194:197]
	ds_read_b128 v[238:241], v125 offset:40960
	s_waitcnt lgkmcnt(0)
	v_mfma_f32_16x16x32_bf16 v[198:201], v[238:241], v[56:59], v[198:201]
	ds_read_b128 v[238:241], v125 offset:49152
	s_waitcnt lgkmcnt(0)
	v_mfma_f32_16x16x32_bf16 v[202:205], v[238:241], v[56:59], v[202:205]
	ds_read_b128 v[238:241], v125 offset:57344
	s_waitcnt lgkmcnt(0)
	v_mfma_f32_16x16x32_bf16 v[206:209], v[238:241], v[56:59], v[206:209]
	ds_read_b128 v[238:241], v153
	ds_read_b128 v[152:155], v152
	s_waitcnt lgkmcnt(0)
	v_mfma_f32_16x16x32_bf16 v[152:155], v[152:155], v[56:59], v[160:163]
	s_nop 2
	ds_read_b128 v[160:163], v151
	s_waitcnt lgkmcnt(0)
	v_mfma_f32_16x16x32_bf16 v[160:163], v[160:163], v[56:59], v[214:217]
	s_nop 2
	ds_read_b128 v[214:217], v150
	s_waitcnt lgkmcnt(0)
	v_mfma_f32_16x16x32_bf16 v[214:217], v[214:217], v[56:59], v[218:221]
	s_nop 2
	ds_read_b128 v[218:221], v149
	ds_read_b128 v[148:151], v148
	s_waitcnt lgkmcnt(0)
	v_mfma_f32_16x16x32_bf16 v[148:151], v[148:151], v[56:59], v[156:159]
	s_nop 2
	ds_read_b128 v[156:159], v147
	s_waitcnt lgkmcnt(0)
	v_mfma_f32_16x16x32_bf16 v[156:159], v[156:159], v[56:59], v[234:237]
	s_nop 2
	ds_read_b128 v[234:237], v146
	v_mfma_f32_16x16x32_bf16 v[210:213], v[238:241], v[56:59], v[210:213]
	v_mfma_f32_16x16x32_bf16 v[218:221], v[218:221], v[56:59], v[246:249]
	s_waitcnt lgkmcnt(0)
	v_mfma_f32_16x16x32_bf16 v[56:59], v[234:237], v[56:59], v[174:177]
	s_nop 2
	ds_read_b128 v[174:177], v126
	s_waitcnt vmcnt(5) lgkmcnt(0)
	v_mfma_f32_16x16x32_bf16 v[174:177], v[174:177], v[52:55], v[178:181]
	s_nop 2
	ds_read_b128 v[178:181], v126 offset:8192
	s_waitcnt lgkmcnt(0)
	v_mfma_f32_16x16x32_bf16 v[178:181], v[178:181], v[52:55], v[182:185]
	s_nop 2
	ds_read_b128 v[182:185], v126 offset:16384
	s_waitcnt lgkmcnt(0)
; #define LAS __attribute__((address_space(3)))
; template <class Sched> __device__ __forceinline__ void att_phase(LAS unsigned char* lds, const bf16_t* Kl, const bf16_t* Vl, const bf16_t* Qb, bf16_t* Ob, const Sched& S, int tid) {
;     ...
;             for (int s = 0; s < 8; ++s)
; #pragma unroll
;                 for (int kb = 0; kb < 16; ++kb) { const bf16x8_t af = *(const LAS bf16x8_t*)(fbase + kb * 8192 + (((4 * s + kg) ^ j) << 4));
;                     acc[kb] = __builtin_amdgcn_mfma_f32_16x16x32_bf16(af, qf[s], acc[kb], 0, 0, 0); }
	v_mfma_f32_16x16x32_bf16 v[182:185], v[182:185], v[52:55], v[186:189]
	s_nop 2
	ds_read_b128 v[186:189], v126 offset:24576
	s_waitcnt lgkmcnt(0)
	v_mfma_f32_16x16x32_bf16 v[186:189], v[186:189], v[52:55], v[190:193]
	s_nop 2
	ds_read_b128 v[190:193], v126 offset:32768
	s_waitcnt lgkmcnt(0)
	v_mfma_f32_16x16x32_bf16 v[190:193], v[190:193], v[52:55], v[194:197]
	s_nop 2
	ds_read_b128 v[194:197], v126 offset:40960
	s_waitcnt lgkmcnt(0)
	v_mfma_f32_16x16x32_bf16 v[194:197], v[194:197], v[52:55], v[198:201]
	s_nop 2
	ds_read_b128 v[198:201], v126 offset:49152
	s_waitcnt lgkmcnt(0)
	v_mfma_f32_16x16x32_bf16 v[198:201], v[198:201], v[52:55], v[202:205]
	s_nop 2
	ds_read_b128 v[202:205], v126 offset:57344
	s_waitcnt lgkmcnt(0)
	v_mfma_f32_16x16x32_bf16 v[202:205], v[202:205], v[52:55], v[206:209]
	s_nop 2
	ds_read_b128 v[206:209], v145
	ds_read_b128 v[144:147], v144
	s_waitcnt lgkmcnt(0)
	v_mfma_f32_16x16x32_bf16 v[144:147], v[144:147], v[52:55], v[152:155]
	s_nop 2
	ds_read_b128 v[152:155], v113
	s_waitcnt lgkmcnt(0)
	v_mfma_f32_16x16x32_bf16 v[152:155], v[152:155], v[52:55], v[160:163]
	s_nop 2
	ds_read_b128 v[160:163], v112
	s_waitcnt lgkmcnt(0)
	v_mfma_f32_16x16x32_bf16 v[160:163], v[160:163], v[52:55], v[214:217]
	s_nop 2
	ds_read_b128 v[214:217], v104
	v_mfma_f32_16x16x32_bf16 v[206:209], v[206:209], v[52:55], v[210:213]
	s_nop 2
	ds_read_b128 v[210:213], v105
	s_waitcnt lgkmcnt(1)
	v_mfma_f32_16x16x32_bf16 v[148:151], v[214:217], v[52:55], v[148:151]
	ds_read_b128 v[214:217], v103
	ds_read_b128 v[102:105], v102
	s_waitcnt lgkmcnt(2)
	v_mfma_f32_16x16x32_bf16 v[210:213], v[210:213], v[52:55], v[218:221]
	s_waitcnt lgkmcnt(1)
	v_mfma_f32_16x16x32_bf16 v[156:159], v[214:217], v[52:55], v[156:159]
	s_waitcnt lgkmcnt(0)
	v_mfma_f32_16x16x32_bf16 v[52:55], v[102:105], v[52:55], v[56:59]
	ds_read_b128 v[102:105], v127 offset:8192
	s_nop 1
	ds_read_b128 v[56:59], v127
	s_waitcnt vmcnt(4) lgkmcnt(1)
	v_mfma_f32_16x16x32_bf16 v[102:105], v[102:105], v[48:51], v[178:181]
	s_nop 2
	ds_read_b128 v[178:181], v127 offset:24576
	s_waitcnt lgkmcnt(0)
	v_mfma_f32_16x16x32_bf16 v[178:181], v[178:181], v[48:51], v[186:189]
	s_nop 2
	ds_read_b128 v[186:189], v127 offset:40960
	v_mfma_f32_16x16x32_bf16 v[56:59], v[56:59], v[48:51], v[174:177]
	s_nop 2
	ds_read_b128 v[174:177], v127 offset:16384
	s_waitcnt lgkmcnt(1)
	v_mfma_f32_16x16x32_bf16 v[186:189], v[186:189], v[48:51], v[194:197]
	s_nop 2
	ds_read_b128 v[194:197], v127 offset:57344
	s_waitcnt lgkmcnt(1)
	v_mfma_f32_16x16x32_bf16 v[174:177], v[174:177], v[48:51], v[182:185]
	s_nop 2
	ds_read_b128 v[182:185], v127 offset:32768
	s_waitcnt lgkmcnt(1)
	v_mfma_f32_16x16x32_bf16 v[194:197], v[194:197], v[48:51], v[202:205]
	s_nop 2
	ds_read_b128 v[202:205], v100
	s_waitcnt lgkmcnt(1)
	v_mfma_f32_16x16x32_bf16 v[182:185], v[182:185], v[48:51], v[190:193]
	s_nop 2
	ds_read_b128 v[190:193], v127 offset:49152
	s_waitcnt lgkmcnt(0)
	v_mfma_f32_16x16x32_bf16 v[190:193], v[190:193], v[48:51], v[198:201]
	s_nop 2
	ds_read_b128 v[198:201], v101
	v_mfma_f32_16x16x32_bf16 v[144:147], v[202:205], v[48:51], v[144:147]
	ds_read_b128 v[202:205], v99
	ds_read_b128 v[98:101], v98
	s_waitcnt lgkmcnt(1)
	v_mfma_f32_16x16x32_bf16 v[152:155], v[202:205], v[48:51], v[152:155]
	ds_read_b128 v[202:205], v96
	s_waitcnt lgkmcnt(1)
	v_mfma_f32_16x16x32_bf16 v[98:101], v[98:101], v[48:51], v[160:163]
	s_nop 2
	ds_read_b128 v[160:163], v97
	s_waitcnt lgkmcnt(1)
	v_mfma_f32_16x16x32_bf16 v[148:151], v[202:205], v[48:51], v[148:151]
	ds_read_b128 v[202:205], v95
	ds_read_b128 v[94:97], v94
	v_mfma_f32_16x16x32_bf16 v[198:201], v[198:201], v[48:51], v[206:209]
	s_waitcnt lgkmcnt(2)
	v_mfma_f32_16x16x32_bf16 v[160:163], v[160:163], v[48:51], v[210:213]
	s_waitcnt lgkmcnt(1)
	v_mfma_f32_16x16x32_bf16 v[156:159], v[202:205], v[48:51], v[156:159]
	s_waitcnt lgkmcnt(0)
	v_mfma_f32_16x16x32_bf16 v[48:51], v[94:97], v[48:51], v[52:55]
	ds_read_b128 v[94:97], v128 offset:16384
	s_nop 1
	ds_read_b128 v[52:55], v128
	s_waitcnt vmcnt(3) lgkmcnt(0)
	v_mfma_f32_16x16x32_bf16 v[52:55], v[52:55], v[44:47], v[56:59]
	s_nop 2
	ds_read_b128 v[56:59], v128 offset:8192
	s_waitcnt lgkmcnt(0)
	v_mfma_f32_16x16x32_bf16 v[56:59], v[56:59], v[44:47], v[102:105]
	s_nop 2
	ds_read_b128 v[102:105], v128 offset:24576
	s_waitcnt lgkmcnt(0)
	v_mfma_f32_16x16x32_bf16 v[102:105], v[102:105], v[44:47], v[178:181]
	s_nop 2
	ds_read_b128 v[178:181], v128 offset:40960
	v_mfma_f32_16x16x32_bf16 v[94:97], v[94:97], v[44:47], v[174:177]
	s_nop 2
	ds_read_b128 v[174:177], v128 offset:32768
	s_waitcnt lgkmcnt(1)
	v_mfma_f32_16x16x32_bf16 v[178:181], v[178:181], v[44:47], v[186:189]
	s_nop 2
	ds_read_b128 v[186:189], v128 offset:57344
	s_waitcnt lgkmcnt(0)
	v_mfma_f32_16x16x32_bf16 v[186:189], v[186:189], v[44:47], v[194:197]
	s_nop 2
	ds_read_b128 v[194:197], v92
	v_mfma_f32_16x16x32_bf16 v[174:177], v[174:177], v[44:47], v[182:185]
	s_nop 2
	ds_read_b128 v[182:185], v128 offset:49152
	s_waitcnt lgkmcnt(0)
	v_mfma_f32_16x16x32_bf16 v[182:185], v[182:185], v[44:47], v[190:193]
	s_nop 2
	ds_read_b128 v[190:193], v93
	v_mfma_f32_16x16x32_bf16 v[144:147], v[194:197], v[44:47], v[144:147]
	ds_read_b128 v[194:197], v91
	ds_read_b128 v[90:93], v90
	s_waitcnt lgkmcnt(0)
	v_mfma_f32_16x16x32_bf16 v[90:93], v[90:93], v[44:47], v[98:101]
	s_nop 2
	ds_read_b128 v[98:101], v89
	s_waitcnt lgkmcnt(0)
	v_mfma_f32_16x16x32_bf16 v[98:101], v[98:101], v[44:47], v[160:163]
	s_nop 2
	ds_read_b128 v[160:163], v88
	s_waitcnt lgkmcnt(0)
	v_mfma_f32_16x16x32_bf16 v[148:151], v[160:163], v[44:47], v[148:151]
	ds_read_b128 v[160:163], v87
	ds_read_b128 v[86:89], v86
	s_waitcnt lgkmcnt(1)
; #define LAS __attribute__((address_space(3)))
; template <class Sched> __device__ __forceinline__ void att_phase(LAS unsigned char* lds, const bf16_t* Kl, const bf16_t* Vl, const bf16_t* Qb, bf16_t* Ob, const Sched& S, int tid) {
;     ...
;             for (int s = 0; s < 8; ++s)
; #pragma unroll
;                 for (int kb = 0; kb < 16; ++kb) { const bf16x8_t af = *(const LAS bf16x8_t*)(fbase + kb * 8192 + (((4 * s + kg) ^ j) << 4));
;                     acc[kb] = __builtin_amdgcn_mfma_f32_16x16x32_bf16(af, qf[s], acc[kb], 0, 0, 0); }
	v_mfma_f32_16x16x32_bf16 v[156:159], v[160:163], v[44:47], v[156:159]
	ds_read_b128 v[160:163], v129 offset:49152
	v_mfma_f32_16x16x32_bf16 v[190:193], v[190:193], v[44:47], v[198:201]
	v_mfma_f32_16x16x32_bf16 v[152:155], v[194:197], v[44:47], v[152:155]
	s_waitcnt vmcnt(2) lgkmcnt(0)
	v_mfma_f32_16x16x32_bf16 v[160:163], v[160:163], v[40:43], v[182:185]
	s_nop 2
	ds_read_b128 v[182:185], v84
	v_mfma_f32_16x16x32_bf16 v[44:47], v[86:89], v[44:47], v[48:51]
	ds_read_b128 v[86:89], v129 offset:24576
	s_waitcnt lgkmcnt(0)
	v_mfma_f32_16x16x32_bf16 v[86:89], v[86:89], v[40:43], v[102:105]
	s_nop 2
	ds_read_b128 v[102:105], v129 offset:40960
	ds_read_b128 v[48:51], v129
	s_waitcnt lgkmcnt(1)
	v_mfma_f32_16x16x32_bf16 v[102:105], v[102:105], v[40:43], v[178:181]
	s_nop 2
	ds_read_b128 v[178:181], v85
	v_mfma_f32_16x16x32_bf16 v[144:147], v[182:185], v[40:43], v[144:147]
	ds_read_b128 v[182:185], v83
	ds_read_b128 v[82:85], v82
	s_waitcnt lgkmcnt(0)
	v_mfma_f32_16x16x32_bf16 v[82:85], v[82:85], v[40:43], v[90:93]
	s_nop 2
	ds_read_b128 v[90:93], v81
	s_waitcnt lgkmcnt(0)
	v_mfma_f32_16x16x32_bf16 v[90:93], v[90:93], v[40:43], v[98:101]
	s_nop 2
	ds_read_b128 v[98:101], v80
	s_waitcnt lgkmcnt(0)
	v_mfma_f32_16x16x32_bf16 v[98:101], v[98:101], v[40:43], v[148:151]
	s_nop 2
	ds_read_b128 v[148:151], v79
	ds_read_b128 v[78:81], v78
	v_mfma_f32_16x16x32_bf16 v[48:51], v[48:51], v[40:43], v[52:55]
	s_nop 2
	ds_read_b128 v[52:55], v129 offset:8192
	s_waitcnt lgkmcnt(0)
	v_mfma_f32_16x16x32_bf16 v[52:55], v[52:55], v[40:43], v[56:59]
	s_nop 2
	ds_read_b128 v[56:59], v129 offset:16384
	s_waitcnt lgkmcnt(0)
	v_mfma_f32_16x16x32_bf16 v[56:59], v[56:59], v[40:43], v[94:97]
	s_nop 2
	ds_read_b128 v[94:97], v129 offset:32768
	s_waitcnt lgkmcnt(0)
	v_mfma_f32_16x16x32_bf16 v[94:97], v[94:97], v[40:43], v[174:177]
	s_nop 2
	ds_read_b128 v[174:177], v129 offset:57344
	s_waitcnt lgkmcnt(0)
	v_mfma_f32_16x16x32_bf16 v[174:177], v[174:177], v[40:43], v[186:189]
	v_mfma_f32_16x16x32_bf16 v[178:181], v[178:181], v[40:43], v[190:193]
	v_mfma_f32_16x16x32_bf16 v[152:155], v[182:185], v[40:43], v[152:155]
	v_mfma_f32_16x16x32_bf16 v[148:151], v[148:151], v[40:43], v[156:159]
	v_mfma_f32_16x16x32_bf16 v[40:43], v[78:81], v[40:43], v[44:47]
	ds_read_b128 v[78:81], v139 offset:32768
	s_waitcnt vmcnt(1) lgkmcnt(0)
	v_mfma_f32_16x16x32_bf16 v[78:81], v[78:81], v[36:39], v[94:97]
	s_nop 2
	ds_read_b128 v[94:97], v139 offset:49152
	ds_read_b128 v[44:47], v139
	s_waitcnt lgkmcnt(1)
	v_mfma_f32_16x16x32_bf16 v[156:159], v[94:97], v[36:39], v[160:163]
	ds_read_b128 v[94:97], v139 offset:57344
	s_waitcnt lgkmcnt(0)
	v_mfma_f32_16x16x32_bf16 v[160:163], v[94:97], v[36:39], v[174:177]
	ds_read_b128 v[94:97], v77
	s_waitcnt lgkmcnt(0)
	v_mfma_f32_16x16x32_bf16 v[174:177], v[94:97], v[36:39], v[178:181]
	ds_read_b128 v[94:97], v76
	s_waitcnt lgkmcnt(0)
	v_mfma_f32_16x16x32_bf16 v[144:147], v[94:97], v[36:39], v[144:147]
	ds_read_b128 v[94:97], v75
	ds_read_b128 v[74:77], v74
	s_waitcnt lgkmcnt(0)
	v_mfma_f32_16x16x32_bf16 v[74:77], v[74:77], v[36:39], v[82:85]
	s_nop 2
	ds_read_b128 v[82:85], v73
	s_waitcnt lgkmcnt(0)
	v_mfma_f32_16x16x32_bf16 v[178:181], v[82:85], v[36:39], v[90:93]
	ds_read_b128 v[82:85], v72
	s_waitcnt lgkmcnt(0)
	v_mfma_f32_16x16x32_bf16 v[182:185], v[82:85], v[36:39], v[98:101]
	ds_read_b128 v[82:85], v71
	ds_read_b128 v[70:73], v70
	v_mfma_f32_16x16x32_bf16 v[44:47], v[44:47], v[36:39], v[48:51]
	s_nop 2
	ds_read_b128 v[48:51], v139 offset:8192
	s_waitcnt lgkmcnt(0)
	v_mfma_f32_16x16x32_bf16 v[48:51], v[48:51], v[36:39], v[52:55]
	s_nop 2
	ds_read_b128 v[52:55], v139 offset:16384
	s_waitcnt lgkmcnt(0)
	v_mfma_f32_16x16x32_bf16 v[52:55], v[52:55], v[36:39], v[56:59]
	s_nop 2
	ds_read_b128 v[56:59], v139 offset:24576
	s_waitcnt lgkmcnt(0)
	v_mfma_f32_16x16x32_bf16 v[56:59], v[56:59], v[36:39], v[86:89]
	s_nop 2
	ds_read_b128 v[86:89], v139 offset:40960
	s_waitcnt lgkmcnt(0)
	v_mfma_f32_16x16x32_bf16 v[86:89], v[86:89], v[36:39], v[102:105]
	v_mfma_f32_16x16x32_bf16 v[152:155], v[94:97], v[36:39], v[152:155]
	v_mfma_f32_16x16x32_bf16 v[148:151], v[82:85], v[36:39], v[148:151]
	v_mfma_f32_16x16x32_bf16 v[186:189], v[70:73], v[36:39], v[40:43]
	ds_read_b128 v[36:39], v141
	s_waitcnt vmcnt(0) lgkmcnt(0)
	v_mfma_f32_16x16x32_bf16 v[98:101], v[36:39], v[32:35], v[44:47]
	ds_read_b128 v[36:39], v141 offset:8192
	s_nop 1
	ds_read_b128 v[44:47], v141 offset:40960
	ds_read_b128 v[40:43], v141 offset:24576
	s_waitcnt lgkmcnt(2)
	v_mfma_f32_16x16x32_bf16 v[102:105], v[36:39], v[32:35], v[48:51]
	ds_read_b128 v[36:39], v141 offset:16384
	s_waitcnt lgkmcnt(2)
	v_mfma_f32_16x16x32_bf16 v[90:93], v[44:47], v[32:35], v[86:89]
	ds_read_b128 v[44:47], v141 offset:49152
	s_waitcnt lgkmcnt(1)
	v_mfma_f32_16x16x32_bf16 v[36:39], v[36:39], v[32:35], v[52:55]
	s_nop 2
	ds_read_b128 v[50:53], v68
	s_waitcnt lgkmcnt(1)
	v_mfma_f32_16x16x32_bf16 v[82:85], v[44:47], v[32:35], v[156:159]
	ds_read_b128 v[44:47], v141 offset:57344
	v_mfma_f32_16x16x32_bf16 v[94:97], v[40:43], v[32:35], v[56:59]
	ds_read_b128 v[40:43], v141 offset:32768
	s_nop 1
	ds_read_b128 v[56:59], v66
	s_waitcnt lgkmcnt(2)
	v_mfma_f32_16x16x32_bf16 v[86:89], v[44:47], v[32:35], v[160:163]
	ds_read_b128 v[44:47], v69
	s_waitcnt lgkmcnt(2)
	v_mfma_f32_16x16x32_bf16 v[40:43], v[40:43], v[32:35], v[78:81]
	v_mfma_f32_16x16x32_bf16 v[78:81], v[50:53], v[32:35], v[144:147]
	ds_read_b128 v[50:53], v67
	s_waitcnt lgkmcnt(2)
	v_mfma_f32_16x16x32_bf16 v[74:77], v[56:59], v[32:35], v[74:77]
	ds_read_b128 v[56:59], v65
	s_waitcnt lgkmcnt(0)
	v_mfma_f32_16x16x32_bf16 v[66:69], v[56:59], v[32:35], v[178:181]
	ds_read_b128 v[56:59], v64
	s_waitcnt lgkmcnt(0)
; #define LAS __attribute__((address_space(3)))
; __device__ __forceinline__ unsigned cvtpk(float lo, float hi) { unsigned r; asm volatile("v_cvt_pk_bf16_f32 %0, %1, %2" : "=v"(r) : "v"(lo), "v"(hi)); return r; }
; template <class Sched> __device__ __forceinline__ void att_phase(LAS unsigned char* lds, const bf16_t* Kl, const bf16_t* Vl, const bf16_t* Qb, bf16_t* Ob, const Sched& S, int tid) {
;     ...
;             for (int s = 0; s < 8; ++s)
; #pragma unroll
;                 for (int kb = 0; kb < 16; ++kb) { const bf16x8_t af = *(const LAS bf16x8_t*)(fbase + kb * 8192 + (((4 * s + kg) ^ j) << 4));
;                     acc[kb] = __builtin_amdgcn_mfma_f32_16x16x32_bf16(af, qf[s], acc[kb], 0, 0, 0); }
;             float mx = acc[0][0];
; #pragma unroll
;             for (int kb = 0; kb < 16; ++kb) mx = fmaxf(fmaxf(mx, fmaxf(acc[kb][0], acc[kb][1])), fmaxf(acc[kb][2], acc[kb][3]));
;             mx = fmaxf(mx, __shfl_xor(mx, 16)); mx = fmaxf(mx, __shfl_xor(mx, 32));
;             const float mxc = mx * cs; float sum = 0.f;
; #pragma unroll
;             for (int t = 0; t < 8; ++t) { f32x4 p0, p1;
; #pragma unroll
;                 for (int e = 0; e < 4; ++e) { p0[e] = __builtin_amdgcn_exp2f(acc[2 * t][e] * cs - mxc); p1[e] = __builtin_amdgcn_exp2f(acc[2 * t + 1][e] * cs - mxc); }
;                 sum += (p0[0] + p0[1]) + (p0[2] + p0[3]) + (p1[0] + p1[1]) + (p1[2] + p1[3]);
;                 u32x4 w; w.x = cvtpk(p0[0], p0[1]); w.y = cvtpk(p0[2], p0[3]); w.z = cvtpk(p1[0], p1[1]); w.w = cvtpk(p1[2], p1[3]); pf[hf][t] = __builtin_bit_cast(bf16x8_t, w); }
	v_mfma_f32_16x16x32_bf16 v[70:73], v[56:59], v[32:35], v[182:185]
	ds_read_b128 v[56:59], v63
	ds_read_b128 v[62:65], v62
	v_mfma_f32_16x16x32_bf16 v[46:49], v[44:47], v[32:35], v[174:177]
	v_mfma_f32_16x16x32_bf16 v[52:55], v[50:53], v[32:35], v[152:155]
	s_waitcnt lgkmcnt(1)
	v_mfma_f32_16x16x32_bf16 v[58:61], v[56:59], v[32:35], v[148:151]
	s_waitcnt lgkmcnt(0)
	v_mfma_f32_16x16x32_bf16 v[62:65], v[62:65], v[32:35], v[186:189]
	v_max_f32_e32 v32, v101, v101
	v_max_f32_e32 v33, v100, v100
	v_max_f32_e32 v32, v33, v32
	v_max_f32_e32 v33, v103, v103
	v_max_f32_e32 v34, v102, v102
	v_max_f32_e32 v33, v34, v33
	v_max_f32_e32 v34, v105, v105
	v_max_f32_e32 v35, v104, v104
	v_max3_f32 v32, v98, v99, v32
	v_max_f32_e32 v34, v35, v34
	v_max3_f32 v32, v32, v33, v34
	v_max_f32_e32 v33, v37, v37
	v_max_f32_e32 v34, v36, v36
	v_max_f32_e32 v33, v34, v33
	v_max_f32_e32 v34, v39, v39
	v_max_f32_e32 v35, v38, v38
	v_max_f32_e32 v34, v35, v34
	v_max3_f32 v32, v32, v33, v34
	v_max_f32_e32 v33, v95, v95
	v_max_f32_e32 v34, v94, v94
	v_max_f32_e32 v33, v34, v33
	v_max_f32_e32 v34, v97, v97
	v_max_f32_e32 v35, v96, v96
	v_max_f32_e32 v34, v35, v34
	v_max3_f32 v32, v32, v33, v34
	v_max_f32_e32 v33, v41, v41
	v_max_f32_e32 v34, v40, v40
	v_max_f32_e32 v33, v34, v33
	v_max_f32_e32 v34, v43, v43
	v_max_f32_e32 v35, v42, v42
	v_max_f32_e32 v34, v35, v34
	v_max3_f32 v32, v32, v33, v34
	v_max_f32_e32 v33, v91, v91
	v_max_f32_e32 v34, v90, v90
	v_max_f32_e32 v33, v34, v33
	v_max_f32_e32 v34, v93, v93
	v_max_f32_e32 v35, v92, v92
	v_max_f32_e32 v34, v35, v34
	v_max3_f32 v32, v32, v33, v34
	v_max_f32_e32 v33, v83, v83
	v_max_f32_e32 v34, v82, v82
	v_max_f32_e32 v33, v34, v33
	v_max_f32_e32 v34, v85, v85
	v_max_f32_e32 v35, v84, v84
	v_max_f32_e32 v34, v35, v34
	v_max3_f32 v32, v32, v33, v34
	v_max_f32_e32 v33, v87, v87
	v_max_f32_e32 v34, v86, v86
	v_max_f32_e32 v33, v34, v33
	v_max_f32_e32 v34, v89, v89
	v_max_f32_e32 v35, v88, v88
	v_max_f32_e32 v34, v35, v34
	v_max3_f32 v32, v32, v33, v34
	v_max_f32_e32 v33, v47, v47
	v_max_f32_e32 v34, v46, v46
	v_max_f32_e32 v33, v34, v33
	v_max_f32_e32 v34, v49, v49
	v_max_f32_e32 v35, v48, v48
	v_max_f32_e32 v34, v35, v34
	v_max3_f32 v32, v32, v33, v34
	v_max_f32_e32 v33, v79, v79
	v_max_f32_e32 v34, v78, v78
	v_max_f32_e32 v33, v34, v33
	v_max_f32_e32 v34, v81, v81
	v_max_f32_e32 v35, v80, v80
	v_max_f32_e32 v34, v35, v34
	v_max3_f32 v32, v32, v33, v34
	v_max_f32_e32 v33, v53, v53
	v_max_f32_e32 v34, v52, v52
	v_max_f32_e32 v33, v34, v33
	v_max_f32_e32 v34, v55, v55
	v_max_f32_e32 v35, v54, v54
	v_max_f32_e32 v34, v35, v34
	v_max3_f32 v32, v32, v33, v34
	v_max_f32_e32 v33, v75, v75
	v_max_f32_e32 v34, v74, v74
	v_max_f32_e32 v33, v34, v33
	v_max_f32_e32 v34, v77, v77
	v_max_f32_e32 v35, v76, v76
	v_max_f32_e32 v34, v35, v34
	v_max3_f32 v32, v32, v33, v34
	v_max_f32_e32 v33, v67, v67
	v_max_f32_e32 v34, v66, v66
	v_max_f32_e32 v33, v34, v33
	v_max_f32_e32 v34, v69, v69
	v_max_f32_e32 v35, v68, v68
	v_max_f32_e32 v34, v35, v34
	v_max3_f32 v32, v32, v33, v34
	v_max_f32_e32 v33, v71, v71
	v_max_f32_e32 v34, v70, v70
	v_max_f32_e32 v33, v34, v33
	v_max_f32_e32 v34, v73, v73
	v_max_f32_e32 v35, v72, v72
	v_max_f32_e32 v34, v35, v34
	v_max3_f32 v32, v32, v33, v34
	v_max_f32_e32 v33, v59, v59
	v_max_f32_e32 v34, v58, v58
	v_max_f32_e32 v33, v34, v33
	v_max_f32_e32 v34, v61, v61
	v_max_f32_e32 v35, v60, v60
	v_max_f32_e32 v34, v35, v34
	v_max3_f32 v32, v32, v33, v34
	v_max_f32_e32 v33, v63, v63
	v_max_f32_e32 v34, v62, v62
	v_max_f32_e32 v33, v34, v33
	v_max_f32_e32 v34, v65, v65
	v_max_f32_e32 v35, v64, v64
	v_max_f32_e32 v34, v35, v34
	v_max3_f32 v32, v32, v33, v34
	ds_bpermute_b32 v33, v142, v32
	s_waitcnt lgkmcnt(0)
	v_max_f32_e32 v33, v33, v33
	v_max_f32_e32 v32, v32, v33
	ds_bpermute_b32 v33, v143, v32
	s_waitcnt lgkmcnt(0)
	v_max_f32_e32 v33, v33, v33
	v_max_f32_e32 v33, v32, v33
	v_mov_b32_e32 v32, v64
	v_pk_mul_f32 v[112:113], v[32:33], s[80:81] op_sel_hi:[1,0]
	s_nop 0
	v_fma_f32 v32, v98, s80, -v113
	v_exp_f32_e32 v45, v32
	v_fma_f32 v32, v102, s80, -v113
	v_exp_f32_e32 v51, v32
	v_fma_f32 v32, v99, s80, -v113
	v_exp_f32_e32 v57, v32
	v_fma_f32 v32, v103, s80, -v113
	v_exp_f32_e32 v99, v32
	v_fma_f32 v32, v100, s80, -v113
	v_exp_f32_e32 v103, v32
	v_fma_f32 v32, v104, s80, -v113
	v_exp_f32_e32 v145, v32
	v_fma_f32 v32, v101, s80, -v113
	v_exp_f32_e32 v101, v32
	v_fma_f32 v32, v105, s80, -v113
	v_exp_f32_e32 v105, v32
	v_fma_f32 v32, v36, s80, -v113
	v_exp_f32_e32 v44, v32
	v_fma_f32 v32, v94, s80, -v113
	v_exp_f32_e32 v50, v32
	v_fma_f32 v32, v37, s80, -v113
	v_exp_f32_e32 v56, v32
	v_fma_f32 v32, v95, s80, -v113
	v_exp_f32_e32 v98, v32
	v_fma_f32 v32, v38, s80, -v113
	v_exp_f32_e32 v102, v32
	v_fma_f32 v32, v96, s80, -v113
	v_exp_f32_e32 v144, v32
	v_fma_f32 v32, v39, s80, -v113
	v_exp_f32_e32 v100, v32
	v_fma_f32 v32, v97, s80, -v113
	v_exp_f32_e32 v104, v32
	v_pk_add_f32 v[32:33], v[44:45], v[56:57]
	v_pk_add_f32 v[34:35], v[102:103], v[100:101]
	v_fma_f32 v41, v41, s80, -v113
	v_pk_add_f32 v[32:33], v[32:33], v[34:35]
	v_pk_add_f32 v[34:35], v[50:51], v[98:99]
	v_fma_f32 v40, v40, s80, -v113
	v_pk_add_f32 v[32:33], v[34:35], v[32:33]
	v_pk_add_f32 v[34:35], v[144:145], v[104:105]
	v_exp_f32_e32 v40, v40
	v_pk_add_f32 v[36:37], v[34:35], v[32:33]
	v_cvt_pk_bf16_f32 v32, v45, v57
	v_cvt_pk_bf16_f32 v33, v103, v101
	v_cvt_pk_bf16_f32 v34, v51, v99
	v_cvt_pk_bf16_f32 v35, v145, v105
	v_fma_f32 v46, v46, s80, -v113
	v_add_f32_e32 v37, 0, v37
	v_add_f32_e32 v57, v36, v37
	v_cvt_pk_bf16_f32 v36, v44, v56
	v_cvt_pk_bf16_f32 v37, v102, v100
	v_cvt_pk_bf16_f32 v38, v50, v98
	v_exp_f32_e32 v50, v41
	v_fma_f32 v41, v91, s80, -v113
; __device__ __forceinline__ unsigned cvtpk(float lo, float hi) { unsigned r; asm volatile("v_cvt_pk_bf16_f32 %0, %1, %2" : "=v"(r) : "v"(lo), "v"(hi)); return r; }
; template <class Sched> __device__ __forceinline__ void att_phase(LAS unsigned char* lds, const bf16_t* Kl, const bf16_t* Vl, const bf16_t* Qb, bf16_t* Ob, const Sched& S, int tid) {
;     ...
;             const float mxc = mx * cs; float sum = 0.f;
; #pragma unroll
;             for (int t = 0; t < 8; ++t) { f32x4 p0, p1;
; #pragma unroll
;                 for (int e = 0; e < 4; ++e) { p0[e] = __builtin_amdgcn_exp2f(acc[2 * t][e] * cs - mxc); p1[e] = __builtin_amdgcn_exp2f(acc[2 * t + 1][e] * cs - mxc); }
;                 sum += (p0[0] + p0[1]) + (p0[2] + p0[3]) + (p1[0] + p1[1]) + (p1[2] + p1[3]);
;                 u32x4 w; w.x = cvtpk(p0[0], p0[1]); w.y = cvtpk(p0[2], p0[3]); w.z = cvtpk(p1[0], p1[1]); w.w = cvtpk(p1[2], p1[3]); pf[hf][t] = __builtin_bit_cast(bf16x8_t, w); }
;             sum += __shfl_xor(sum, 16); sum += __shfl_xor(sum, 32);
;             inv[hf] = 1.f / sum;
;             __builtin_amdgcn_sched_barrier(0);
;         }
;         __syncthreads();
;         att_stage(lds, Vl + (size_t)(h * 256) * 1024 + b * 256, 1024, tid);
	v_fma_f32 v44, v90, s80, -v113
	v_exp_f32_e32 v91, v41
	v_fma_f32 v41, v42, s80, -v113
	v_fma_f32 v42, v92, s80, -v113
	v_exp_f32_e32 v45, v44
	v_exp_f32_e32 v44, v42
	v_fma_f32 v42, v43, s80, -v113
	v_exp_f32_e32 v41, v41
	v_exp_f32_e32 v51, v42
	v_fma_f32 v42, v93, s80, -v113
	v_exp_f32_e32 v90, v42
	v_cvt_pk_bf16_f32 v39, v144, v104
	v_pk_add_f32 v[42:43], v[40:41], v[50:51]
	v_cvt_pk_bf16_f32 v40, v40, v50
	v_pk_add_f32 v[92:93], v[44:45], v[90:91]
	v_pk_add_f32 v[42:43], v[42:43], v[42:43] op_sel:[0,1] op_sel_hi:[1,0]
	v_cvt_pk_bf16_f32 v41, v41, v51
	v_fma_f32 v50, v87, s80, -v113
	v_pk_add_f32 v[42:43], v[92:93], v[42:43] op_sel:[1,0] op_sel_hi:[0,1]
	v_pk_add_f32 v[92:93], v[92:93], v[42:43]
	v_cvt_pk_bf16_f32 v42, v45, v91
	v_fma_f32 v45, v86, s80, -v113
	v_fma_f32 v56, v88, s80, -v113
	v_cvt_pk_bf16_f32 v43, v44, v90
	v_fma_f32 v44, v82, s80, -v113
	v_exp_f32_e32 v51, v45
	v_fma_f32 v45, v83, s80, -v113
	v_exp_f32_e32 v83, v50
	v_fma_f32 v50, v84, s80, -v113
	v_exp_f32_e32 v87, v56
	v_fma_f32 v56, v85, s80, -v113
	v_exp_f32_e32 v44, v44
	v_exp_f32_e32 v45, v45
	v_exp_f32_e32 v50, v50
	v_exp_f32_e32 v56, v56
	v_fma_f32 v64, v89, s80, -v113
	v_add_f32_e32 v89, v44, v45
	v_cvt_pk_bf16_f32 v44, v44, v45
	v_add_f32_e32 v91, v50, v56
	v_cvt_pk_bf16_f32 v45, v50, v56
	v_exp_f32_e32 v50, v46
	v_fma_f32 v46, v78, s80, -v113
	v_exp_f32_e32 v86, v46
	v_fma_f32 v46, v47, s80, -v113
	v_exp_f32_e32 v82, v46
	v_fma_f32 v46, v79, s80, -v113
	v_exp_f32_e32 v84, v46
	v_fma_f32 v46, v48, s80, -v113
	v_exp_f32_e32 v88, v46
	v_fma_f32 v46, v80, s80, -v113
	v_exp_f32_e32 v78, v46
	v_fma_f32 v46, v49, s80, -v113
	v_exp_f32_e32 v90, v46
	v_exp_f32_e32 v85, v64
	v_fma_f32 v46, v81, s80, -v113
	v_exp_f32_e32 v56, v46
	v_pk_add_f32 v[48:49], v[50:51], v[82:83]
	v_pk_add_f32 v[80:81], v[88:89], v[90:91]
	v_mov_b32_e32 v79, v92
	v_pk_add_f32 v[48:49], v[48:49], v[80:81]
	v_pk_add_f32 v[80:81], v[86:87], v[84:85]
	v_fma_f32 v53, v53, s80, -v113
	v_pk_add_f32 v[48:49], v[80:81], v[48:49]
	v_pk_add_f32 v[80:81], v[78:79], v[56:57]
	v_cvt_pk_bf16_f32 v46, v51, v83
	v_cvt_pk_bf16_f32 v47, v87, v85
	v_fma_f32 v52, v52, s80, -v113
	v_pk_add_f32 v[48:49], v[48:49], v[80:81]
	v_exp_f32_e32 v52, v52
	v_pk_add_f32 v[80:81], v[48:49], v[48:49] op_sel_hi:[0,1]
	v_cvt_pk_bf16_f32 v48, v50, v82
	v_cvt_pk_bf16_f32 v49, v88, v90
	v_cvt_pk_bf16_f32 v50, v86, v84
	v_cvt_pk_bf16_f32 v51, v78, v56
	v_fma_f32 v56, v74, s80, -v113
	v_exp_f32_e32 v74, v53
	v_fma_f32 v53, v75, s80, -v113
	v_exp_f32_e32 v79, v53
	v_fma_f32 v53, v54, s80, -v113
	v_fma_f32 v54, v76, s80, -v113
	v_exp_f32_e32 v57, v56
	v_exp_f32_e32 v56, v54
	v_fma_f32 v54, v55, s80, -v113
	v_exp_f32_e32 v53, v53
	v_exp_f32_e32 v75, v54
	v_fma_f32 v54, v77, s80, -v113
	v_exp_f32_e32 v78, v54
	v_fma_f32 v64, v71, s80, -v113
	v_pk_add_f32 v[54:55], v[52:53], v[74:75]
	v_cvt_pk_bf16_f32 v52, v52, v74
	v_pk_add_f32 v[76:77], v[56:57], v[78:79]
	v_pk_add_f32 v[54:55], v[54:55], v[54:55] op_sel:[0,1] op_sel_hi:[1,0]
	v_cvt_pk_bf16_f32 v53, v53, v75
	v_fma_f32 v58, v58, s80, -v113
	v_pk_add_f32 v[54:55], v[76:77], v[54:55] op_sel:[1,0] op_sel_hi:[0,1]
	v_pk_add_f32 v[76:77], v[76:77], v[54:55]
	v_cvt_pk_bf16_f32 v54, v57, v79
	v_cvt_pk_bf16_f32 v55, v56, v78
	v_fma_f32 v56, v66, s80, -v113
	v_fma_f32 v57, v70, s80, -v113
	v_fma_f32 v66, v72, s80, -v113
	v_exp_f32_e32 v75, v57
	v_fma_f32 v57, v67, s80, -v113
	v_exp_f32_e32 v67, v64
	v_fma_f32 v64, v68, s80, -v113
	v_exp_f32_e32 v71, v66
	v_fma_f32 v66, v69, s80, -v113
	v_exp_f32_e32 v56, v56
	v_exp_f32_e32 v57, v57
	v_exp_f32_e32 v64, v64
	v_exp_f32_e32 v66, v66
	v_exp_f32_e32 v74, v58
	v_fma_f32 v58, v62, s80, -v113
	v_exp_f32_e32 v70, v58
	v_fma_f32 v58, v59, s80, -v113
	v_fma_f32 v68, v73, s80, -v113
	v_add_f32_e32 v73, v56, v57
	v_add_f32_e32 v79, v64, v66
	v_cvt_pk_bf16_f32 v56, v56, v57
	v_cvt_pk_bf16_f32 v57, v64, v66
	v_exp_f32_e32 v66, v58
	v_fma_f32 v58, v63, s80, -v113
	v_exp_f32_e32 v69, v68
	v_exp_f32_e32 v68, v58
	v_fma_f32 v58, v60, s80, -v113
	v_exp_f32_e32 v72, v58
	v_sub_f32_e32 v58, v112, v113
	v_exp_f32_e32 v64, v58
	v_fma_f32 v58, v61, s80, -v113
	v_exp_f32_e32 v78, v58
	v_fma_f32 v58, v65, s80, -v113
	v_exp_f32_e32 v80, v58
	v_pk_add_f32 v[60:61], v[74:75], v[66:67]
	v_pk_add_f32 v[62:63], v[72:73], v[78:79]
	v_mov_b32_e32 v65, v76
	v_pk_add_f32 v[60:61], v[60:61], v[62:63]
	v_pk_add_f32 v[62:63], v[70:71], v[68:69]
	v_cvt_pk_bf16_f32 v58, v75, v67
	v_cvt_pk_bf16_f32 v59, v71, v69
	s_nop 0
	v_pk_add_f32 v[60:61], v[62:63], v[60:61]
	v_pk_add_f32 v[62:63], v[64:65], v[80:81]
	s_nop 0
	v_pk_add_f32 v[60:61], v[60:61], v[62:63]
	s_nop 0
	v_add_f32_e32 v65, v60, v61
	v_cvt_pk_bf16_f32 v60, v74, v66
	v_cvt_pk_bf16_f32 v61, v72, v78
	v_cvt_pk_bf16_f32 v62, v70, v68
	v_cvt_pk_bf16_f32 v63, v64, v80
	ds_bpermute_b32 v64, v142, v65
	s_waitcnt lgkmcnt(0)
	v_add_f32_e32 v64, v65, v64
	ds_bpermute_b32 v65, v143, v64
	s_waitcnt lgkmcnt(0)
	v_add_f32_e32 v64, v64, v65
	v_div_scale_f32 v65, s[6:7], v64, v64, 1.0
	v_rcp_f32_e32 v66, v65
	s_nop 0
	v_fma_f32 v67, -v65, v66, 1.0
	v_fmac_f32_e32 v66, v67, v66
	v_div_scale_f32 v67, vcc, 1.0, v64, 1.0
	v_mul_f32_e32 v68, v67, v66
	v_fma_f32 v69, -v65, v68, v67
	v_fmac_f32_e32 v68, v69, v66
	v_fma_f32 v65, -v65, v68, v67
	v_div_fmas_f32 v65, v65, v66, v68
	v_div_fixup_f32 v68, v65, v64, 1.0
	s_lshl_b64 s[6:7], s[10:11], 11
	v_readlane_b32 s10, v254, 22
	s_add_u32 s6, s10, s6
	v_readlane_b32 s10, v254, 23
	s_addc_u32 s7, s10, s7
	s_lshl_b64 s[4:5], s[4:5], 1
	s_add_u32 s4, s6, s4
	s_addc_u32 s5, s7, s5
	v_lshlrev_b64 v[64:65], 11, v[108:109]
	v_lshl_add_u64 v[64:65], s[4:5], 0, v[64:65]
	v_lshl_add_u64 v[108:109], v[64:65], 0, v[164:165]
	s_mov_b32 s4, 0x8000
	v_add_co_u32_e32 v70, vcc, s4, v108
	s_mov_b32 s4, 0x10000
	s_nop 0
	v_addc_co_u32_e32 v71, vcc, 0, v109, vcc
	v_add_co_u32_e32 v74, vcc, s4, v108
	s_mov_b32 s4, 0x18000
	s_nop 0
	v_addc_co_u32_e32 v75, vcc, 0, v109, vcc
	v_add_co_u32_e32 v78, vcc, s4, v108
	s_mov_b32 s4, 0x28000
	s_nop 0
	v_addc_co_u32_e32 v79, vcc, 0, v109, vcc
	v_add_co_u32_e32 v82, vcc, s16, v108
	s_nop 1
	v_addc_co_u32_e32 v83, vcc, 0, v109, vcc
	v_add_co_u32_e32 v86, vcc, s4, v108
	s_mov_b32 s4, 0x30000
	s_nop 0
	v_addc_co_u32_e32 v87, vcc, 0, v109, vcc
	v_add_co_u32_e32 v90, vcc, s4, v108
	s_mov_b32 s4, 0x38000
	s_nop 0
	v_addc_co_u32_e32 v91, vcc, 0, v109, vcc
	v_add_co_u32_e32 v94, vcc, s4, v108
	s_mov_b32 s4, 0x48000
	s_nop 0
	v_addc_co_u32_e32 v95, vcc, 0, v109, vcc
	v_add_co_u32_e32 v98, vcc, s15, v108
	s_barrier
; #define LAS __attribute__((address_space(3)))
; __device__ __forceinline__ unsigned cvtpk(float lo, float hi) { unsigned r; asm volatile("v_cvt_pk_bf16_f32 %0, %1, %2" : "=v"(r) : "v"(lo), "v"(hi)); return r; }
; __device__ __forceinline__ void att_stage(LAS unsigned char* lds, const bf16_t* src, int pitch, int tid) {
;     const int r0 = tid >> 5, ch = tid & 31;
;     const bf16_t* g0 = src + (size_t)r0 * pitch + ch * 8;
;     LAS unsigned char* l0 = lds + r0 * 512 + ((ch ^ r0) << 4);
;     u32x4 v[16];
; #pragma unroll
;     for (int x = 0; x < 16; ++x) v[x] = *(const u32x4*)(g0 + (size_t)(16 * x) * pitch);
; #pragma unroll
;     for (int x = 0; x < 16; ++x) *(LAS u32x4*)(l0 + x * 8192) = v[x];
; }
; template <class Sched> __device__ __forceinline__ void att_phase(LAS unsigned char* lds, const bf16_t* Kl, const bf16_t* Vl, const bf16_t* Qb, bf16_t* Ob, const Sched& S, int tid) {
;     ...
;         att_stage(lds, Vl + (size_t)(h * 256) * 1024 + b * 256, 1024, tid);
;         __syncthreads();
; #pragma unroll
;         for (int db = 0; db < 16; ++db) {
;             f32x4 o0 = (f32x4){0.f, 0.f, 0.f, 0.f}, o1 = o0;
; #pragma unroll
;             for (int t = 0; t < 8; ++t) { const bf16x8_t af = *(const LAS bf16x8_t*)(fbase + db * 8192 + (((4 * t + kg) ^ j) << 4));
;                 o0 = __builtin_amdgcn_mfma_f32_16x16x32_bf16(af, pf[0][t], o0, 0, 0, 0); o1 = __builtin_amdgcn_mfma_f32_16x16x32_bf16(af, pf[1][t], o1, 0, 0, 0); }
;             u32x2_t w; w.x = cvtpk(o0[0] * inv[0], o0[1] * inv[0]); w.y = cvtpk(o0[2] * inv[0], o0[3] * inv[0]);
;             *(u32x2_t*)(orow + 16 * db + 4 * kg) = w;
;             w.x = cvtpk(o1[0] * inv[1], o1[1] * inv[1]); w.y = cvtpk(o1[2] * inv[1], o1[3] * inv[1]);
;             *(u32x2_t*)(orow + (size_t)128 * 1024 + 16 * db + 4 * kg) = w;
	s_nop 0
	v_addc_co_u32_e32 v99, vcc, 0, v109, vcc
	v_add_co_u32_e32 v102, vcc, s4, v108
	s_mov_b32 s4, 0x50000
	s_nop 0
	v_addc_co_u32_e32 v103, vcc, 0, v109, vcc
	v_add_co_u32_e32 v112, vcc, s4, v108
	s_mov_b32 s4, 0x58000
	s_nop 0
	v_addc_co_u32_e32 v113, vcc, 0, v109, vcc
	v_add_co_u32_e32 v146, vcc, s4, v108
	s_nop 1
	v_addc_co_u32_e32 v147, vcc, 0, v109, vcc
	s_add_i32 m0, m0, 0xfffe2000
	s_nop 0
	global_load_lds_dwordx4 v[108:109], off
	s_nop 0
	s_add_i32 m0, m0, 0x2000
	s_nop 0
	global_load_lds_dwordx4 v[70:71], off
	s_nop 0
	s_add_i32 m0, m0, 0x2000
	s_nop 0
	global_load_lds_dwordx4 v[74:75], off
	s_nop 0
	s_add_i32 m0, m0, 0x2000
	s_nop 0
	global_load_lds_dwordx4 v[78:79], off
	s_nop 0
	s_add_i32 m0, m0, 0x2000
	s_nop 0
	global_load_lds_dwordx4 v[82:83], off
	s_nop 0
	s_add_i32 m0, m0, 0x2000
	s_nop 0
	global_load_lds_dwordx4 v[86:87], off
	s_nop 0
	s_add_i32 m0, m0, 0x2000
	s_nop 0
	global_load_lds_dwordx4 v[90:91], off
	s_nop 0
	s_add_i32 m0, m0, 0x2000
	s_nop 0
	global_load_lds_dwordx4 v[94:95], off
	s_nop 0
	s_add_i32 m0, m0, 0x2000
	s_nop 0
	global_load_lds_dwordx4 v[98:99], off
	s_nop 0
	s_add_i32 m0, m0, 0x2000
	s_nop 0
	global_load_lds_dwordx4 v[102:103], off
	s_nop 0
	s_add_i32 m0, m0, 0x2000
	s_nop 0
	global_load_lds_dwordx4 v[112:113], off
	s_nop 0
	s_add_i32 m0, m0, 0x2000
	s_nop 0
	global_load_lds_dwordx4 v[146:147], off
	v_add_co_u32_e32 v112, vcc, s17, v108
	s_mov_b32 s4, 0x68000
	s_nop 0
	v_addc_co_u32_e32 v113, vcc, 0, v109, vcc
	v_add_co_u32_e32 v154, vcc, s4, v108
	s_mov_b32 s4, 0x70000
	s_nop 0
	v_addc_co_u32_e32 v155, vcc, 0, v109, vcc
	s_add_i32 m0, m0, 0x2000
	s_nop 0
	global_load_lds_dwordx4 v[112:113], off
	s_nop 0
	s_add_i32 m0, m0, 0x2000
	s_nop 0
	global_load_lds_dwordx4 v[154:155], off
	v_add_co_u32_e32 v112, vcc, s4, v108
	s_mov_b32 s4, 0x78000
	s_nop 0
	v_addc_co_u32_e32 v113, vcc, 0, v109, vcc
	v_add_co_u32_e32 v108, vcc, s4, v108
	s_mov_b64 s[4:5], 0x40000
	s_nop 0
	v_addc_co_u32_e32 v109, vcc, 0, v109, vcc
	s_add_i32 m0, m0, 0x2000
	s_nop 0
	global_load_lds_dwordx4 v[112:113], off
	s_add_i32 m0, m0, 0x2000
	s_nop 0
	global_load_lds_dwordx4 v[108:109], off
	s_add_u32 s8, s8, s50
	s_addc_u32 s9, s9, s51
	s_waitcnt vmcnt(0)
	s_waitcnt lgkmcnt(0)
	s_barrier
	ds_read_b128 v[64:67], v124
	ds_read_b128 v[70:73], v125
	s_waitcnt lgkmcnt(1)
	v_mfma_f32_16x16x32_bf16 v[74:77], v[64:67], v[0:3], 0
	v_mfma_f32_16x16x32_bf16 v[64:67], v[64:67], v[32:35], 0
	s_waitcnt lgkmcnt(0)
	v_mfma_f32_16x16x32_bf16 v[74:77], v[70:73], v[4:7], v[74:77]
	v_mfma_f32_16x16x32_bf16 v[64:67], v[70:73], v[36:39], v[64:67]
	ds_read_b128 v[70:73], v126
	ds_read_b128 v[78:81], v127
	s_waitcnt lgkmcnt(1)
	v_mfma_f32_16x16x32_bf16 v[74:77], v[70:73], v[8:11], v[74:77]
	v_mfma_f32_16x16x32_bf16 v[64:67], v[70:73], v[40:43], v[64:67]
	s_waitcnt lgkmcnt(0)
	v_mfma_f32_16x16x32_bf16 v[70:73], v[78:81], v[12:15], v[74:77]
	v_mfma_f32_16x16x32_bf16 v[64:67], v[78:81], v[44:47], v[64:67]
	s_nop 3
	ds_read_b128 v[74:77], v128
	ds_read_b128 v[78:81], v129
	s_waitcnt lgkmcnt(1)
	v_mfma_f32_16x16x32_bf16 v[70:73], v[74:77], v[16:19], v[70:73]
	v_mfma_f32_16x16x32_bf16 v[64:67], v[74:77], v[48:51], v[64:67]
	s_waitcnt lgkmcnt(0)
	v_mfma_f32_16x16x32_bf16 v[70:73], v[78:81], v[20:23], v[70:73]
	v_mfma_f32_16x16x32_bf16 v[64:67], v[78:81], v[52:55], v[64:67]
	ds_read_b128 v[74:77], v139
	ds_read_b128 v[78:81], v141
	s_waitcnt lgkmcnt(1)
	v_mfma_f32_16x16x32_bf16 v[70:73], v[74:77], v[24:27], v[70:73]
	v_mfma_f32_16x16x32_bf16 v[74:77], v[74:77], v[56:59], v[64:67]
	s_waitcnt lgkmcnt(0)
	v_mfma_f32_16x16x32_bf16 v[70:73], v[78:81], v[28:31], v[70:73]
	s_nop 0
	v_lshl_add_u64 v[64:65], v[106:107], 0, v[110:111]
	v_mfma_f32_16x16x32_bf16 v[74:77], v[78:81], v[60:63], v[74:77]
	s_nop 4
	v_mul_f32_e32 v66, v140, v70
	v_mul_f32_e32 v67, v140, v71
	v_cvt_pk_bf16_f32 v66, v66, v67
	v_mul_f32_e32 v67, v140, v72
	v_mul_f32_e32 v69, v140, v73
	v_cvt_pk_bf16_f32 v67, v67, v69
	global_store_dwordx2 v[64:65], v[66:67], off
	v_mul_f32_e32 v66, v68, v74
	v_mul_f32_e32 v67, v68, v75
	v_cvt_pk_bf16_f32 v66, v66, v67
	v_mul_f32_e32 v67, v68, v76
	v_mul_f32_e32 v69, v68, v77
	v_cvt_pk_bf16_f32 v67, v67, v69
	ds_read_b128 v[70:73], v124 offset:8192
	ds_read_b128 v[74:77], v125 offset:8192
	s_waitcnt lgkmcnt(1)
	v_mfma_f32_16x16x32_bf16 v[78:81], v[70:73], v[0:3], 0
	v_mfma_f32_16x16x32_bf16 v[70:73], v[70:73], v[32:35], 0
	s_waitcnt lgkmcnt(0)
	v_mfma_f32_16x16x32_bf16 v[78:81], v[74:77], v[4:7], v[78:81]
	v_mfma_f32_16x16x32_bf16 v[70:73], v[74:77], v[36:39], v[70:73]
	ds_read_b128 v[74:77], v126 offset:8192
	ds_read_b128 v[82:85], v127 offset:8192
	s_waitcnt lgkmcnt(1)
	v_mfma_f32_16x16x32_bf16 v[78:81], v[74:77], v[8:11], v[78:81]
	v_mfma_f32_16x16x32_bf16 v[70:73], v[74:77], v[40:43], v[70:73]
	s_waitcnt lgkmcnt(0)
	v_mfma_f32_16x16x32_bf16 v[74:77], v[82:85], v[12:15], v[78:81]
	v_mfma_f32_16x16x32_bf16 v[70:73], v[82:85], v[44:47], v[70:73]
	s_nop 3
	ds_read_b128 v[78:81], v128 offset:8192
	ds_read_b128 v[82:85], v129 offset:8192
	s_waitcnt lgkmcnt(1)
	v_mfma_f32_16x16x32_bf16 v[74:77], v[78:81], v[16:19], v[74:77]
	v_mfma_f32_16x16x32_bf16 v[70:73], v[78:81], v[48:51], v[70:73]
	s_waitcnt lgkmcnt(0)
	v_mfma_f32_16x16x32_bf16 v[74:77], v[82:85], v[20:23], v[74:77]
	v_mfma_f32_16x16x32_bf16 v[70:73], v[82:85], v[52:55], v[70:73]
	ds_read_b128 v[78:81], v139 offset:8192
	ds_read_b128 v[82:85], v141 offset:8192
	s_waitcnt lgkmcnt(1)
	v_mfma_f32_16x16x32_bf16 v[74:77], v[78:81], v[24:27], v[74:77]
	v_mfma_f32_16x16x32_bf16 v[70:73], v[78:81], v[56:59], v[70:73]
	v_add_co_u32_e32 v78, vcc, s15, v64
	s_waitcnt lgkmcnt(0)
; #define LAS __attribute__((address_space(3)))
; __device__ __forceinline__ unsigned cvtpk(float lo, float hi) { unsigned r; asm volatile("v_cvt_pk_bf16_f32 %0, %1, %2" : "=v"(r) : "v"(lo), "v"(hi)); return r; }
; template <class Sched> __device__ __forceinline__ void att_phase(LAS unsigned char* lds, const bf16_t* Kl, const bf16_t* Vl, const bf16_t* Qb, bf16_t* Ob, const Sched& S, int tid) {
;     ...
; #pragma unroll
;         for (int db = 0; db < 16; ++db) {
;             f32x4 o0 = (f32x4){0.f, 0.f, 0.f, 0.f}, o1 = o0;
; #pragma unroll
;             for (int t = 0; t < 8; ++t) { const bf16x8_t af = *(const LAS bf16x8_t*)(fbase + db * 8192 + (((4 * t + kg) ^ j) << 4));
;                 o0 = __builtin_amdgcn_mfma_f32_16x16x32_bf16(af, pf[0][t], o0, 0, 0, 0); o1 = __builtin_amdgcn_mfma_f32_16x16x32_bf16(af, pf[1][t], o1, 0, 0, 0); }
;             u32x2_t w; w.x = cvtpk(o0[0] * inv[0], o0[1] * inv[0]); w.y = cvtpk(o0[2] * inv[0], o0[3] * inv[0]);
;             *(u32x2_t*)(orow + 16 * db + 4 * kg) = w;
;             w.x = cvtpk(o1[0] * inv[1], o1[1] * inv[1]); w.y = cvtpk(o1[2] * inv[1], o1[3] * inv[1]);
;             *(u32x2_t*)(orow + (size_t)128 * 1024 + 16 * db + 4 * kg) = w;
	v_mfma_f32_16x16x32_bf16 v[74:77], v[82:85], v[28:31], v[74:77]
	v_addc_co_u32_e32 v79, vcc, 0, v65, vcc
	global_store_dwordx2 v[78:79], v[66:67], off
	v_mfma_f32_16x16x32_bf16 v[70:73], v[82:85], v[60:63], v[70:73]
	s_nop 4
	v_mul_f32_e32 v66, v140, v74
	v_mul_f32_e32 v67, v140, v75
	v_cvt_pk_bf16_f32 v66, v66, v67
	v_mul_f32_e32 v67, v140, v76
	v_mul_f32_e32 v69, v140, v77
	v_cvt_pk_bf16_f32 v67, v67, v69
	global_store_dwordx2 v[64:65], v[66:67], off offset:32
	v_mul_f32_e32 v66, v68, v70
	v_mul_f32_e32 v67, v68, v71
	v_cvt_pk_bf16_f32 v86, v66, v67
	v_mul_f32_e32 v66, v68, v72
	v_mul_f32_e32 v67, v68, v73
	v_cvt_pk_bf16_f32 v87, v66, v67
	ds_read_b128 v[70:73], v124 offset:16384
	ds_read_b128 v[74:77], v125 offset:16384
	s_waitcnt lgkmcnt(1)
	v_mfma_f32_16x16x32_bf16 v[78:81], v[70:73], v[0:3], 0
	v_lshl_add_u64 v[66:67], v[64:65], 0, s[4:5]
	s_mov_b64 s[4:5], 0
	v_mfma_f32_16x16x32_bf16 v[70:73], v[70:73], v[32:35], 0
	s_waitcnt lgkmcnt(0)
	v_mfma_f32_16x16x32_bf16 v[78:81], v[74:77], v[4:7], v[78:81]
	v_mfma_f32_16x16x32_bf16 v[70:73], v[74:77], v[36:39], v[70:73]
	ds_read_b128 v[74:77], v126 offset:16384
	ds_read_b128 v[82:85], v127 offset:16384
	s_waitcnt lgkmcnt(1)
	v_mfma_f32_16x16x32_bf16 v[78:81], v[74:77], v[8:11], v[78:81]
	v_mfma_f32_16x16x32_bf16 v[70:73], v[74:77], v[40:43], v[70:73]
	s_waitcnt lgkmcnt(0)
	v_mfma_f32_16x16x32_bf16 v[74:77], v[82:85], v[12:15], v[78:81]
	v_mfma_f32_16x16x32_bf16 v[70:73], v[82:85], v[44:47], v[70:73]
	s_nop 3
	ds_read_b128 v[78:81], v128 offset:16384
	ds_read_b128 v[82:85], v129 offset:16384
	s_waitcnt lgkmcnt(1)
	v_mfma_f32_16x16x32_bf16 v[74:77], v[78:81], v[16:19], v[74:77]
	v_mfma_f32_16x16x32_bf16 v[70:73], v[78:81], v[48:51], v[70:73]
	s_waitcnt lgkmcnt(0)
	v_mfma_f32_16x16x32_bf16 v[74:77], v[82:85], v[20:23], v[74:77]
	v_mfma_f32_16x16x32_bf16 v[70:73], v[82:85], v[52:55], v[70:73]
	ds_read_b128 v[78:81], v139 offset:16384
	ds_read_b128 v[82:85], v141 offset:16384
	global_store_dwordx2 v[66:67], v[86:87], off offset:32
	s_waitcnt lgkmcnt(1)
	v_mfma_f32_16x16x32_bf16 v[74:77], v[78:81], v[24:27], v[74:77]
	v_mfma_f32_16x16x32_bf16 v[70:73], v[78:81], v[56:59], v[70:73]
	s_waitcnt lgkmcnt(0)
	v_mfma_f32_16x16x32_bf16 v[74:77], v[82:85], v[28:31], v[74:77]
	v_mfma_f32_16x16x32_bf16 v[70:73], v[82:85], v[60:63], v[70:73]
	s_nop 6
	v_mul_f32_e32 v69, v140, v74
	v_mul_f32_e32 v74, v140, v75
	v_mul_f32_e32 v75, v140, v76
	v_cvt_pk_bf16_f32 v74, v69, v74
	v_mul_f32_e32 v69, v140, v77
	v_cvt_pk_bf16_f32 v75, v75, v69
	v_mul_f32_e32 v69, v68, v70
	v_mul_f32_e32 v70, v68, v71
	global_store_dwordx2 v[64:65], v[74:75], off offset:64
	v_cvt_pk_bf16_f32 v86, v69, v70
	v_mul_f32_e32 v70, v68, v73
	v_mul_f32_e32 v69, v68, v72
	v_cvt_pk_bf16_f32 v87, v69, v70
	ds_read_b128 v[70:73], v124 offset:24576
	ds_read_b128 v[74:77], v125 offset:24576
	s_waitcnt lgkmcnt(1)
	v_mfma_f32_16x16x32_bf16 v[78:81], v[70:73], v[0:3], 0
	v_mfma_f32_16x16x32_bf16 v[70:73], v[70:73], v[32:35], 0
	s_waitcnt lgkmcnt(0)
	v_mfma_f32_16x16x32_bf16 v[78:81], v[74:77], v[4:7], v[78:81]
	v_mfma_f32_16x16x32_bf16 v[70:73], v[74:77], v[36:39], v[70:73]
	ds_read_b128 v[74:77], v126 offset:24576
	ds_read_b128 v[82:85], v127 offset:24576
	s_waitcnt lgkmcnt(1)
	v_mfma_f32_16x16x32_bf16 v[78:81], v[74:77], v[8:11], v[78:81]
	v_mfma_f32_16x16x32_bf16 v[70:73], v[74:77], v[40:43], v[70:73]
	s_waitcnt lgkmcnt(0)
	v_mfma_f32_16x16x32_bf16 v[74:77], v[82:85], v[12:15], v[78:81]
	v_mfma_f32_16x16x32_bf16 v[70:73], v[82:85], v[44:47], v[70:73]
	s_nop 3
	ds_read_b128 v[78:81], v128 offset:24576
	ds_read_b128 v[82:85], v129 offset:24576
	s_waitcnt lgkmcnt(1)
	v_mfma_f32_16x16x32_bf16 v[74:77], v[78:81], v[16:19], v[74:77]
	v_mfma_f32_16x16x32_bf16 v[70:73], v[78:81], v[48:51], v[70:73]
	s_waitcnt lgkmcnt(0)
	v_mfma_f32_16x16x32_bf16 v[74:77], v[82:85], v[20:23], v[74:77]
	v_mfma_f32_16x16x32_bf16 v[70:73], v[82:85], v[52:55], v[70:73]
	ds_read_b128 v[78:81], v139 offset:24576
	ds_read_b128 v[82:85], v141 offset:24576
	global_store_dwordx2 v[66:67], v[86:87], off offset:64
	s_waitcnt lgkmcnt(1)
	v_mfma_f32_16x16x32_bf16 v[74:77], v[78:81], v[24:27], v[74:77]
	v_mfma_f32_16x16x32_bf16 v[70:73], v[78:81], v[56:59], v[70:73]
	s_waitcnt lgkmcnt(0)
	v_mfma_f32_16x16x32_bf16 v[74:77], v[82:85], v[28:31], v[74:77]
	v_mfma_f32_16x16x32_bf16 v[70:73], v[82:85], v[60:63], v[70:73]
	s_nop 6
	v_mul_f32_e32 v69, v140, v74
	v_mul_f32_e32 v74, v140, v75
	v_mul_f32_e32 v75, v140, v76
	v_mul_f32_e32 v76, v140, v77
	v_mul_f32_e32 v77, v68, v70
	v_cvt_pk_bf16_f32 v70, v69, v74
	v_mul_f32_e32 v78, v68, v71
	v_cvt_pk_bf16_f32 v71, v75, v76
	global_store_dwordx2 v[64:65], v[70:71], off offset:96
	v_mul_f32_e32 v70, v68, v73
	v_cvt_pk_bf16_f32 v86, v77, v78
	v_mul_f32_e32 v69, v68, v72
	v_cvt_pk_bf16_f32 v87, v69, v70
	ds_read_b128 v[70:73], v124 offset:32768
	ds_read_b128 v[74:77], v125 offset:32768
	s_waitcnt lgkmcnt(1)
	v_mfma_f32_16x16x32_bf16 v[78:81], v[70:73], v[0:3], 0
	v_mfma_f32_16x16x32_bf16 v[70:73], v[70:73], v[32:35], 0
	s_waitcnt lgkmcnt(0)
	v_mfma_f32_16x16x32_bf16 v[78:81], v[74:77], v[4:7], v[78:81]
	v_mfma_f32_16x16x32_bf16 v[70:73], v[74:77], v[36:39], v[70:73]
	ds_read_b128 v[74:77], v126 offset:32768
	ds_read_b128 v[82:85], v127 offset:32768
	s_waitcnt lgkmcnt(1)
	v_mfma_f32_16x16x32_bf16 v[78:81], v[74:77], v[8:11], v[78:81]
	v_mfma_f32_16x16x32_bf16 v[70:73], v[74:77], v[40:43], v[70:73]
	s_waitcnt lgkmcnt(0)
	v_mfma_f32_16x16x32_bf16 v[74:77], v[82:85], v[12:15], v[78:81]
	v_mfma_f32_16x16x32_bf16 v[70:73], v[82:85], v[44:47], v[70:73]
	s_nop 3
	ds_read_b128 v[78:81], v128 offset:32768
	ds_read_b128 v[82:85], v129 offset:32768
	s_waitcnt lgkmcnt(1)
; #define LAS __attribute__((address_space(3)))
; __device__ __forceinline__ unsigned cvtpk(float lo, float hi) { unsigned r; asm volatile("v_cvt_pk_bf16_f32 %0, %1, %2" : "=v"(r) : "v"(lo), "v"(hi)); return r; }
; template <class Sched> __device__ __forceinline__ void att_phase(LAS unsigned char* lds, const bf16_t* Kl, const bf16_t* Vl, const bf16_t* Qb, bf16_t* Ob, const Sched& S, int tid) {
;     ...
; #pragma unroll
;         for (int db = 0; db < 16; ++db) {
;             f32x4 o0 = (f32x4){0.f, 0.f, 0.f, 0.f}, o1 = o0;
; #pragma unroll
;             for (int t = 0; t < 8; ++t) { const bf16x8_t af = *(const LAS bf16x8_t*)(fbase + db * 8192 + (((4 * t + kg) ^ j) << 4));
;                 o0 = __builtin_amdgcn_mfma_f32_16x16x32_bf16(af, pf[0][t], o0, 0, 0, 0); o1 = __builtin_amdgcn_mfma_f32_16x16x32_bf16(af, pf[1][t], o1, 0, 0, 0); }
;             u32x2_t w; w.x = cvtpk(o0[0] * inv[0], o0[1] * inv[0]); w.y = cvtpk(o0[2] * inv[0], o0[3] * inv[0]);
;             *(u32x2_t*)(orow + 16 * db + 4 * kg) = w;
;             w.x = cvtpk(o1[0] * inv[1], o1[1] * inv[1]); w.y = cvtpk(o1[2] * inv[1], o1[3] * inv[1]);
;             *(u32x2_t*)(orow + (size_t)128 * 1024 + 16 * db + 4 * kg) = w;
	v_mfma_f32_16x16x32_bf16 v[74:77], v[78:81], v[16:19], v[74:77]
	v_mfma_f32_16x16x32_bf16 v[70:73], v[78:81], v[48:51], v[70:73]
	s_waitcnt lgkmcnt(0)
	v_mfma_f32_16x16x32_bf16 v[74:77], v[82:85], v[20:23], v[74:77]
	v_mfma_f32_16x16x32_bf16 v[70:73], v[82:85], v[52:55], v[70:73]
	ds_read_b128 v[78:81], v139 offset:32768
	ds_read_b128 v[82:85], v141 offset:32768
	global_store_dwordx2 v[66:67], v[86:87], off offset:96
	s_waitcnt lgkmcnt(1)
	v_mfma_f32_16x16x32_bf16 v[74:77], v[78:81], v[24:27], v[74:77]
	v_mfma_f32_16x16x32_bf16 v[70:73], v[78:81], v[56:59], v[70:73]
	s_waitcnt lgkmcnt(0)
	v_mfma_f32_16x16x32_bf16 v[74:77], v[82:85], v[28:31], v[74:77]
	v_mfma_f32_16x16x32_bf16 v[70:73], v[82:85], v[60:63], v[70:73]
	s_nop 6
	v_mul_f32_e32 v69, v140, v74
	v_mul_f32_e32 v74, v140, v75
	v_cvt_pk_bf16_f32 v74, v69, v74
	v_mul_f32_e32 v69, v140, v76
	v_mul_f32_e32 v75, v140, v77
	v_cvt_pk_bf16_f32 v75, v69, v75
	v_mul_f32_e32 v69, v68, v70
	v_mul_f32_e32 v70, v68, v71
	global_store_dwordx2 v[64:65], v[74:75], off offset:128
	v_cvt_pk_bf16_f32 v86, v69, v70
	v_mul_f32_e32 v70, v68, v73
	v_mul_f32_e32 v69, v68, v72
	v_cvt_pk_bf16_f32 v87, v69, v70
	ds_read_b128 v[70:73], v124 offset:40960
	ds_read_b128 v[74:77], v125 offset:40960
	s_waitcnt lgkmcnt(1)
	v_mfma_f32_16x16x32_bf16 v[78:81], v[70:73], v[0:3], 0
	v_mfma_f32_16x16x32_bf16 v[70:73], v[70:73], v[32:35], 0
	s_waitcnt lgkmcnt(0)
	v_mfma_f32_16x16x32_bf16 v[78:81], v[74:77], v[4:7], v[78:81]
	v_mfma_f32_16x16x32_bf16 v[70:73], v[74:77], v[36:39], v[70:73]
	ds_read_b128 v[74:77], v126 offset:40960
	ds_read_b128 v[82:85], v127 offset:40960
	s_waitcnt lgkmcnt(1)
	v_mfma_f32_16x16x32_bf16 v[78:81], v[74:77], v[8:11], v[78:81]
	v_mfma_f32_16x16x32_bf16 v[70:73], v[74:77], v[40:43], v[70:73]
	s_waitcnt lgkmcnt(0)
	v_mfma_f32_16x16x32_bf16 v[74:77], v[82:85], v[12:15], v[78:81]
	v_mfma_f32_16x16x32_bf16 v[70:73], v[82:85], v[44:47], v[70:73]
	s_nop 3
	ds_read_b128 v[78:81], v128 offset:40960
	ds_read_b128 v[82:85], v129 offset:40960
	s_waitcnt lgkmcnt(1)
	v_mfma_f32_16x16x32_bf16 v[74:77], v[78:81], v[16:19], v[74:77]
	v_mfma_f32_16x16x32_bf16 v[70:73], v[78:81], v[48:51], v[70:73]
	s_waitcnt lgkmcnt(0)
	v_mfma_f32_16x16x32_bf16 v[74:77], v[82:85], v[20:23], v[74:77]
	v_mfma_f32_16x16x32_bf16 v[70:73], v[82:85], v[52:55], v[70:73]
	ds_read_b128 v[78:81], v139 offset:40960
	ds_read_b128 v[82:85], v141 offset:40960
	global_store_dwordx2 v[66:67], v[86:87], off offset:128
	s_waitcnt lgkmcnt(1)
	v_mfma_f32_16x16x32_bf16 v[74:77], v[78:81], v[24:27], v[74:77]
	v_mfma_f32_16x16x32_bf16 v[70:73], v[78:81], v[56:59], v[70:73]
	s_waitcnt lgkmcnt(0)
	v_mfma_f32_16x16x32_bf16 v[74:77], v[82:85], v[28:31], v[74:77]
	v_mfma_f32_16x16x32_bf16 v[70:73], v[82:85], v[60:63], v[70:73]
	s_nop 6
	v_mul_f32_e32 v69, v140, v74
	v_mul_f32_e32 v74, v140, v75
	v_cvt_pk_bf16_f32 v74, v69, v74
	v_mul_f32_e32 v69, v140, v76
	v_mul_f32_e32 v75, v140, v77
	v_cvt_pk_bf16_f32 v75, v69, v75
	v_mul_f32_e32 v69, v68, v70
	v_mul_f32_e32 v70, v68, v71
	global_store_dwordx2 v[64:65], v[74:75], off offset:160
	v_cvt_pk_bf16_f32 v86, v69, v70
	v_mul_f32_e32 v70, v68, v73
	v_mul_f32_e32 v69, v68, v72
	v_cvt_pk_bf16_f32 v87, v69, v70
	ds_read_b128 v[70:73], v124 offset:49152
	ds_read_b128 v[74:77], v125 offset:49152
	s_waitcnt lgkmcnt(1)
	v_mfma_f32_16x16x32_bf16 v[78:81], v[70:73], v[0:3], 0
	v_mfma_f32_16x16x32_bf16 v[70:73], v[70:73], v[32:35], 0
	s_waitcnt lgkmcnt(0)
	v_mfma_f32_16x16x32_bf16 v[78:81], v[74:77], v[4:7], v[78:81]
	v_mfma_f32_16x16x32_bf16 v[70:73], v[74:77], v[36:39], v[70:73]
	ds_read_b128 v[74:77], v126 offset:49152
	ds_read_b128 v[82:85], v127 offset:49152
	s_waitcnt lgkmcnt(1)
	v_mfma_f32_16x16x32_bf16 v[78:81], v[74:77], v[8:11], v[78:81]
	v_mfma_f32_16x16x32_bf16 v[70:73], v[74:77], v[40:43], v[70:73]
	s_waitcnt lgkmcnt(0)
	v_mfma_f32_16x16x32_bf16 v[74:77], v[82:85], v[12:15], v[78:81]
	v_mfma_f32_16x16x32_bf16 v[70:73], v[82:85], v[44:47], v[70:73]
	s_nop 3
	ds_read_b128 v[78:81], v128 offset:49152
	ds_read_b128 v[82:85], v129 offset:49152
	s_waitcnt lgkmcnt(1)
	v_mfma_f32_16x16x32_bf16 v[74:77], v[78:81], v[16:19], v[74:77]
	v_mfma_f32_16x16x32_bf16 v[70:73], v[78:81], v[48:51], v[70:73]
	s_waitcnt lgkmcnt(0)
	v_mfma_f32_16x16x32_bf16 v[74:77], v[82:85], v[20:23], v[74:77]
	v_mfma_f32_16x16x32_bf16 v[70:73], v[82:85], v[52:55], v[70:73]
	ds_read_b128 v[78:81], v139 offset:49152
	ds_read_b128 v[82:85], v141 offset:49152
	global_store_dwordx2 v[66:67], v[86:87], off offset:160
	s_waitcnt lgkmcnt(1)
	v_mfma_f32_16x16x32_bf16 v[74:77], v[78:81], v[24:27], v[74:77]
	v_mfma_f32_16x16x32_bf16 v[70:73], v[78:81], v[56:59], v[70:73]
	s_waitcnt lgkmcnt(0)
	v_mfma_f32_16x16x32_bf16 v[74:77], v[82:85], v[28:31], v[74:77]
	v_mfma_f32_16x16x32_bf16 v[70:73], v[82:85], v[60:63], v[70:73]
	s_nop 6
	v_mul_f32_e32 v69, v140, v74
	v_mul_f32_e32 v74, v140, v75
	v_cvt_pk_bf16_f32 v74, v69, v74
	v_mul_f32_e32 v69, v140, v76
	v_mul_f32_e32 v75, v140, v77
	v_cvt_pk_bf16_f32 v75, v69, v75
	v_mul_f32_e32 v69, v68, v70
	v_mul_f32_e32 v70, v68, v71
	global_store_dwordx2 v[64:65], v[74:75], off offset:192
	v_cvt_pk_bf16_f32 v86, v69, v70
	v_mul_f32_e32 v70, v68, v73
	v_mul_f32_e32 v69, v68, v72
	v_cvt_pk_bf16_f32 v87, v69, v70
	ds_read_b128 v[70:73], v124 offset:57344
	ds_read_b128 v[74:77], v125 offset:57344
	s_waitcnt lgkmcnt(1)
	v_mfma_f32_16x16x32_bf16 v[78:81], v[70:73], v[0:3], 0
	v_mfma_f32_16x16x32_bf16 v[70:73], v[70:73], v[32:35], 0
	s_waitcnt lgkmcnt(0)
	v_mfma_f32_16x16x32_bf16 v[78:81], v[74:77], v[4:7], v[78:81]
	v_mfma_f32_16x16x32_bf16 v[70:73], v[74:77], v[36:39], v[70:73]
	ds_read_b128 v[74:77], v126 offset:57344
	ds_read_b128 v[82:85], v127 offset:57344
	s_waitcnt lgkmcnt(1)
; #define LAS __attribute__((address_space(3)))
; __device__ __forceinline__ unsigned cvtpk(float lo, float hi) { unsigned r; asm volatile("v_cvt_pk_bf16_f32 %0, %1, %2" : "=v"(r) : "v"(lo), "v"(hi)); return r; }
; template <class Sched> __device__ __forceinline__ void att_phase(LAS unsigned char* lds, const bf16_t* Kl, const bf16_t* Vl, const bf16_t* Qb, bf16_t* Ob, const Sched& S, int tid) {
;     ...
; #pragma unroll
;         for (int db = 0; db < 16; ++db) {
;             f32x4 o0 = (f32x4){0.f, 0.f, 0.f, 0.f}, o1 = o0;
; #pragma unroll
;             for (int t = 0; t < 8; ++t) { const bf16x8_t af = *(const LAS bf16x8_t*)(fbase + db * 8192 + (((4 * t + kg) ^ j) << 4));
;                 o0 = __builtin_amdgcn_mfma_f32_16x16x32_bf16(af, pf[0][t], o0, 0, 0, 0); o1 = __builtin_amdgcn_mfma_f32_16x16x32_bf16(af, pf[1][t], o1, 0, 0, 0); }
;             u32x2_t w; w.x = cvtpk(o0[0] * inv[0], o0[1] * inv[0]); w.y = cvtpk(o0[2] * inv[0], o0[3] * inv[0]);
;             *(u32x2_t*)(orow + 16 * db + 4 * kg) = w;
;             w.x = cvtpk(o1[0] * inv[1], o1[1] * inv[1]); w.y = cvtpk(o1[2] * inv[1], o1[3] * inv[1]);
;             *(u32x2_t*)(orow + (size_t)128 * 1024 + 16 * db + 4 * kg) = w;
	v_mfma_f32_16x16x32_bf16 v[78:81], v[74:77], v[8:11], v[78:81]
	v_mfma_f32_16x16x32_bf16 v[70:73], v[74:77], v[40:43], v[70:73]
	s_waitcnt lgkmcnt(0)
	v_mfma_f32_16x16x32_bf16 v[74:77], v[82:85], v[12:15], v[78:81]
	v_mfma_f32_16x16x32_bf16 v[70:73], v[82:85], v[44:47], v[70:73]
	s_nop 3
	ds_read_b128 v[78:81], v128 offset:57344
	ds_read_b128 v[82:85], v129 offset:57344
	s_waitcnt lgkmcnt(1)
	v_mfma_f32_16x16x32_bf16 v[74:77], v[78:81], v[16:19], v[74:77]
	v_mfma_f32_16x16x32_bf16 v[70:73], v[78:81], v[48:51], v[70:73]
	s_waitcnt lgkmcnt(0)
	v_mfma_f32_16x16x32_bf16 v[74:77], v[82:85], v[20:23], v[74:77]
	v_mfma_f32_16x16x32_bf16 v[70:73], v[82:85], v[52:55], v[70:73]
	ds_read_b128 v[78:81], v139 offset:57344
	ds_read_b128 v[82:85], v141 offset:57344
	global_store_dwordx2 v[66:67], v[86:87], off offset:192
	s_waitcnt lgkmcnt(1)
	v_mfma_f32_16x16x32_bf16 v[74:77], v[78:81], v[24:27], v[74:77]
	v_mfma_f32_16x16x32_bf16 v[70:73], v[78:81], v[56:59], v[70:73]
	s_waitcnt lgkmcnt(0)
	v_mfma_f32_16x16x32_bf16 v[74:77], v[82:85], v[28:31], v[74:77]
	v_mfma_f32_16x16x32_bf16 v[70:73], v[82:85], v[60:63], v[70:73]
	s_nop 6
	v_mul_f32_e32 v69, v140, v74
	v_mul_f32_e32 v74, v140, v75
	v_cvt_pk_bf16_f32 v74, v69, v74
	v_mul_f32_e32 v69, v140, v76
	v_mul_f32_e32 v75, v140, v77
	v_cvt_pk_bf16_f32 v75, v69, v75
	v_mul_f32_e32 v69, v68, v70
	global_store_dwordx2 v[64:65], v[74:75], off offset:224
	v_mul_f32_e32 v70, v68, v71
	v_cvt_pk_bf16_f32 v86, v69, v70
	v_mul_f32_e32 v69, v68, v72
	v_mul_f32_e32 v70, v68, v73
	v_cvt_pk_bf16_f32 v87, v69, v70
	v_add_u32_e32 v69, 0x10000, v115
	v_add_u32_e32 v70, v69, v116
	ds_read_b128 v[70:73], v70
	v_add_u32_e32 v74, v69, v117
	ds_read_b128 v[74:77], v74
	s_waitcnt lgkmcnt(1)
	v_mfma_f32_16x16x32_bf16 v[78:81], v[70:73], v[0:3], 0
	v_add_u32_e32 v82, v69, v119
	ds_read_b128 v[82:85], v82
	global_store_dwordx2 v[66:67], v[86:87], off offset:224
	v_mfma_f32_16x16x32_bf16 v[70:73], v[70:73], v[32:35], 0
	s_waitcnt lgkmcnt(1)
	v_mfma_f32_16x16x32_bf16 v[78:81], v[74:77], v[4:7], v[78:81]
	v_mfma_f32_16x16x32_bf16 v[70:73], v[74:77], v[36:39], v[70:73]
	v_add_u32_e32 v74, v69, v118
	ds_read_b128 v[74:77], v74
	s_waitcnt lgkmcnt(0)
	v_mfma_f32_16x16x32_bf16 v[78:81], v[74:77], v[8:11], v[78:81]
	v_mfma_f32_16x16x32_bf16 v[70:73], v[74:77], v[40:43], v[70:73]
	v_mfma_f32_16x16x32_bf16 v[74:77], v[82:85], v[12:15], v[78:81]
	s_nop 5
	v_add_u32_e32 v78, v69, v120
	ds_read_b128 v[78:81], v78
	v_mfma_f32_16x16x32_bf16 v[70:73], v[82:85], v[44:47], v[70:73]
	v_add_u32_e32 v82, v69, v121
	ds_read_b128 v[82:85], v82
	s_waitcnt lgkmcnt(1)
	v_mfma_f32_16x16x32_bf16 v[74:77], v[78:81], v[16:19], v[74:77]
	v_mfma_f32_16x16x32_bf16 v[70:73], v[78:81], v[48:51], v[70:73]
	v_add_u32_e32 v78, v69, v122
	ds_read_b128 v[78:81], v78
	v_add_u32_e32 v69, v69, v123
	s_waitcnt lgkmcnt(1)
	v_mfma_f32_16x16x32_bf16 v[74:77], v[82:85], v[20:23], v[74:77]
	v_mfma_f32_16x16x32_bf16 v[70:73], v[82:85], v[52:55], v[70:73]
	ds_read_b128 v[82:85], v69
	s_waitcnt lgkmcnt(1)
	v_mfma_f32_16x16x32_bf16 v[74:77], v[78:81], v[24:27], v[74:77]
	v_mfma_f32_16x16x32_bf16 v[70:73], v[78:81], v[56:59], v[70:73]
	s_waitcnt lgkmcnt(0)
	v_mfma_f32_16x16x32_bf16 v[74:77], v[82:85], v[28:31], v[74:77]
	v_mfma_f32_16x16x32_bf16 v[70:73], v[82:85], v[60:63], v[70:73]
	s_nop 6
	v_mul_f32_e32 v69, v140, v74
	v_mul_f32_e32 v74, v140, v75
	v_cvt_pk_bf16_f32 v74, v69, v74
	v_mul_f32_e32 v69, v140, v76
	v_mul_f32_e32 v75, v140, v77
	v_cvt_pk_bf16_f32 v75, v69, v75
	v_mul_f32_e32 v69, v68, v70
	global_store_dwordx2 v[64:65], v[74:75], off offset:256
	v_mul_f32_e32 v70, v68, v71
	v_cvt_pk_bf16_f32 v86, v69, v70
	v_mul_f32_e32 v69, v68, v72
	v_mul_f32_e32 v70, v68, v73
	v_cvt_pk_bf16_f32 v87, v69, v70
	v_add_u32_e32 v69, 0x12000, v115
	v_add_u32_e32 v70, v69, v116
	ds_read_b128 v[70:73], v70
	v_add_u32_e32 v74, v69, v117
	ds_read_b128 v[74:77], v74
	s_waitcnt lgkmcnt(1)
	v_mfma_f32_16x16x32_bf16 v[78:81], v[70:73], v[0:3], 0
	v_add_u32_e32 v82, v69, v119
	ds_read_b128 v[82:85], v82
	global_store_dwordx2 v[66:67], v[86:87], off offset:256
	v_mfma_f32_16x16x32_bf16 v[70:73], v[70:73], v[32:35], 0
	s_waitcnt lgkmcnt(1)
	v_mfma_f32_16x16x32_bf16 v[78:81], v[74:77], v[4:7], v[78:81]
	v_mfma_f32_16x16x32_bf16 v[70:73], v[74:77], v[36:39], v[70:73]
	v_add_u32_e32 v74, v69, v118
	ds_read_b128 v[74:77], v74
	s_waitcnt lgkmcnt(0)
	v_mfma_f32_16x16x32_bf16 v[78:81], v[74:77], v[8:11], v[78:81]
	v_mfma_f32_16x16x32_bf16 v[70:73], v[74:77], v[40:43], v[70:73]
	v_mfma_f32_16x16x32_bf16 v[74:77], v[82:85], v[12:15], v[78:81]
	s_nop 5
	v_add_u32_e32 v78, v69, v120
	ds_read_b128 v[78:81], v78
	v_mfma_f32_16x16x32_bf16 v[70:73], v[82:85], v[44:47], v[70:73]
	v_add_u32_e32 v82, v69, v121
	ds_read_b128 v[82:85], v82
	s_waitcnt lgkmcnt(1)
	v_mfma_f32_16x16x32_bf16 v[74:77], v[78:81], v[16:19], v[74:77]
	v_mfma_f32_16x16x32_bf16 v[70:73], v[78:81], v[48:51], v[70:73]
	v_add_u32_e32 v78, v69, v122
	ds_read_b128 v[78:81], v78
	v_add_u32_e32 v69, v69, v123
	s_waitcnt lgkmcnt(1)
	v_mfma_f32_16x16x32_bf16 v[74:77], v[82:85], v[20:23], v[74:77]
	v_mfma_f32_16x16x32_bf16 v[70:73], v[82:85], v[52:55], v[70:73]
	ds_read_b128 v[82:85], v69
	s_waitcnt lgkmcnt(1)
	v_mfma_f32_16x16x32_bf16 v[74:77], v[78:81], v[24:27], v[74:77]
	v_mfma_f32_16x16x32_bf16 v[70:73], v[78:81], v[56:59], v[70:73]
	s_waitcnt lgkmcnt(0)
; #define LAS __attribute__((address_space(3)))
; __device__ __forceinline__ unsigned cvtpk(float lo, float hi) { unsigned r; asm volatile("v_cvt_pk_bf16_f32 %0, %1, %2" : "=v"(r) : "v"(lo), "v"(hi)); return r; }
; template <class Sched> __device__ __forceinline__ void att_phase(LAS unsigned char* lds, const bf16_t* Kl, const bf16_t* Vl, const bf16_t* Qb, bf16_t* Ob, const Sched& S, int tid) {
;     ...
; #pragma unroll
;         for (int db = 0; db < 16; ++db) {
;             f32x4 o0 = (f32x4){0.f, 0.f, 0.f, 0.f}, o1 = o0;
; #pragma unroll
;             for (int t = 0; t < 8; ++t) { const bf16x8_t af = *(const LAS bf16x8_t*)(fbase + db * 8192 + (((4 * t + kg) ^ j) << 4));
;                 o0 = __builtin_amdgcn_mfma_f32_16x16x32_bf16(af, pf[0][t], o0, 0, 0, 0); o1 = __builtin_amdgcn_mfma_f32_16x16x32_bf16(af, pf[1][t], o1, 0, 0, 0); }
;             u32x2_t w; w.x = cvtpk(o0[0] * inv[0], o0[1] * inv[0]); w.y = cvtpk(o0[2] * inv[0], o0[3] * inv[0]);
;             *(u32x2_t*)(orow + 16 * db + 4 * kg) = w;
;             w.x = cvtpk(o1[0] * inv[1], o1[1] * inv[1]); w.y = cvtpk(o1[2] * inv[1], o1[3] * inv[1]);
;             *(u32x2_t*)(orow + (size_t)128 * 1024 + 16 * db + 4 * kg) = w;
;         }
	v_mfma_f32_16x16x32_bf16 v[74:77], v[82:85], v[28:31], v[74:77]
	v_mfma_f32_16x16x32_bf16 v[70:73], v[82:85], v[60:63], v[70:73]
	s_nop 6
	v_mul_f32_e32 v69, v140, v74
	v_mul_f32_e32 v74, v140, v75
	v_cvt_pk_bf16_f32 v74, v69, v74
	v_mul_f32_e32 v69, v140, v76
	v_mul_f32_e32 v75, v140, v77
	v_cvt_pk_bf16_f32 v75, v69, v75
	v_mul_f32_e32 v69, v68, v70
	global_store_dwordx2 v[64:65], v[74:75], off offset:288
	v_mul_f32_e32 v70, v68, v71
	v_cvt_pk_bf16_f32 v86, v69, v70
	v_mul_f32_e32 v69, v68, v72
	v_mul_f32_e32 v70, v68, v73
	v_cvt_pk_bf16_f32 v87, v69, v70
	v_add_u32_e32 v69, 0x14000, v115
	v_add_u32_e32 v70, v69, v116
	ds_read_b128 v[70:73], v70
	v_add_u32_e32 v74, v69, v117
	ds_read_b128 v[74:77], v74
	s_waitcnt lgkmcnt(1)
	v_mfma_f32_16x16x32_bf16 v[78:81], v[70:73], v[0:3], 0
	v_add_u32_e32 v82, v69, v119
	ds_read_b128 v[82:85], v82
	global_store_dwordx2 v[66:67], v[86:87], off offset:288
	v_mfma_f32_16x16x32_bf16 v[70:73], v[70:73], v[32:35], 0
	s_waitcnt lgkmcnt(1)
	v_mfma_f32_16x16x32_bf16 v[78:81], v[74:77], v[4:7], v[78:81]
	v_mfma_f32_16x16x32_bf16 v[70:73], v[74:77], v[36:39], v[70:73]
	v_add_u32_e32 v74, v69, v118
	ds_read_b128 v[74:77], v74
	s_waitcnt lgkmcnt(0)
	v_mfma_f32_16x16x32_bf16 v[78:81], v[74:77], v[8:11], v[78:81]
	v_mfma_f32_16x16x32_bf16 v[70:73], v[74:77], v[40:43], v[70:73]
	v_mfma_f32_16x16x32_bf16 v[74:77], v[82:85], v[12:15], v[78:81]
	s_nop 5
	v_add_u32_e32 v78, v69, v120
	ds_read_b128 v[78:81], v78
	v_mfma_f32_16x16x32_bf16 v[70:73], v[82:85], v[44:47], v[70:73]
	v_add_u32_e32 v82, v69, v121
	ds_read_b128 v[82:85], v82
	s_waitcnt lgkmcnt(1)
	v_mfma_f32_16x16x32_bf16 v[74:77], v[78:81], v[16:19], v[74:77]
	v_mfma_f32_16x16x32_bf16 v[70:73], v[78:81], v[48:51], v[70:73]
	v_add_u32_e32 v78, v69, v122
	ds_read_b128 v[78:81], v78
	v_add_u32_e32 v69, v69, v123
	s_waitcnt lgkmcnt(1)
	v_mfma_f32_16x16x32_bf16 v[74:77], v[82:85], v[20:23], v[74:77]
	v_mfma_f32_16x16x32_bf16 v[70:73], v[82:85], v[52:55], v[70:73]
	ds_read_b128 v[82:85], v69
	s_waitcnt lgkmcnt(1)
	v_mfma_f32_16x16x32_bf16 v[74:77], v[78:81], v[24:27], v[74:77]
	v_mfma_f32_16x16x32_bf16 v[70:73], v[78:81], v[56:59], v[70:73]
	s_waitcnt lgkmcnt(0)
	v_mfma_f32_16x16x32_bf16 v[74:77], v[82:85], v[28:31], v[74:77]
	v_mfma_f32_16x16x32_bf16 v[70:73], v[82:85], v[60:63], v[70:73]
	s_nop 6
	v_mul_f32_e32 v69, v140, v74
	v_mul_f32_e32 v74, v140, v75
	v_cvt_pk_bf16_f32 v74, v69, v74
	v_mul_f32_e32 v69, v140, v76
	v_mul_f32_e32 v75, v140, v77
	v_cvt_pk_bf16_f32 v75, v69, v75
	v_mul_f32_e32 v69, v68, v70
	global_store_dwordx2 v[64:65], v[74:75], off offset:320
	v_mul_f32_e32 v70, v68, v71
	v_cvt_pk_bf16_f32 v86, v69, v70
	v_mul_f32_e32 v69, v68, v72
	v_mul_f32_e32 v70, v68, v73
	v_cvt_pk_bf16_f32 v87, v69, v70
	v_add_u32_e32 v69, 0x16000, v115
	v_add_u32_e32 v70, v69, v116
	ds_read_b128 v[70:73], v70
	v_add_u32_e32 v74, v69, v117
	ds_read_b128 v[74:77], v74
	s_waitcnt lgkmcnt(1)
	v_mfma_f32_16x16x32_bf16 v[78:81], v[70:73], v[0:3], 0
	v_add_u32_e32 v82, v69, v119
	ds_read_b128 v[82:85], v82
	global_store_dwordx2 v[66:67], v[86:87], off offset:320
	v_mfma_f32_16x16x32_bf16 v[70:73], v[70:73], v[32:35], 0
	s_waitcnt lgkmcnt(1)
	v_mfma_f32_16x16x32_bf16 v[78:81], v[74:77], v[4:7], v[78:81]
	v_mfma_f32_16x16x32_bf16 v[70:73], v[74:77], v[36:39], v[70:73]
	v_add_u32_e32 v74, v69, v118
	ds_read_b128 v[74:77], v74
	s_waitcnt lgkmcnt(0)
	v_mfma_f32_16x16x32_bf16 v[78:81], v[74:77], v[8:11], v[78:81]
	v_mfma_f32_16x16x32_bf16 v[70:73], v[74:77], v[40:43], v[70:73]
	v_mfma_f32_16x16x32_bf16 v[74:77], v[82:85], v[12:15], v[78:81]
	s_nop 5
	v_add_u32_e32 v78, v69, v120
	ds_read_b128 v[78:81], v78
	v_mfma_f32_16x16x32_bf16 v[70:73], v[82:85], v[44:47], v[70:73]
	v_add_u32_e32 v82, v69, v121
	ds_read_b128 v[82:85], v82
	s_waitcnt lgkmcnt(1)
	v_mfma_f32_16x16x32_bf16 v[74:77], v[78:81], v[16:19], v[74:77]
	v_mfma_f32_16x16x32_bf16 v[70:73], v[78:81], v[48:51], v[70:73]
	v_add_u32_e32 v78, v69, v122
	ds_read_b128 v[78:81], v78
	v_add_u32_e32 v69, v69, v123
	s_waitcnt lgkmcnt(1)
	v_mfma_f32_16x16x32_bf16 v[74:77], v[82:85], v[20:23], v[74:77]
	v_mfma_f32_16x16x32_bf16 v[70:73], v[82:85], v[52:55], v[70:73]
	ds_read_b128 v[82:85], v69
	s_waitcnt lgkmcnt(1)
	v_mfma_f32_16x16x32_bf16 v[74:77], v[78:81], v[24:27], v[74:77]
	v_mfma_f32_16x16x32_bf16 v[70:73], v[78:81], v[56:59], v[70:73]
	s_waitcnt lgkmcnt(0)
	v_mfma_f32_16x16x32_bf16 v[74:77], v[82:85], v[28:31], v[74:77]
	v_mfma_f32_16x16x32_bf16 v[70:73], v[82:85], v[60:63], v[70:73]
	s_nop 6
	v_mul_f32_e32 v69, v140, v74
	v_mul_f32_e32 v74, v140, v75
	v_cvt_pk_bf16_f32 v74, v69, v74
	v_mul_f32_e32 v69, v140, v76
	v_mul_f32_e32 v75, v140, v77
	v_cvt_pk_bf16_f32 v75, v69, v75
	v_mul_f32_e32 v69, v68, v70
	global_store_dwordx2 v[64:65], v[74:75], off offset:352
	v_mul_f32_e32 v70, v68, v71
	v_cvt_pk_bf16_f32 v86, v69, v70
	v_mul_f32_e32 v69, v68, v72
	v_mul_f32_e32 v70, v68, v73
	v_cvt_pk_bf16_f32 v87, v69, v70
	v_add_u32_e32 v69, 0x18000, v115
	v_add_u32_e32 v70, v69, v116
	ds_read_b128 v[70:73], v70
	v_add_u32_e32 v74, v69, v117
	ds_read_b128 v[74:77], v74
	s_waitcnt lgkmcnt(1)
	v_mfma_f32_16x16x32_bf16 v[78:81], v[70:73], v[0:3], 0
	v_add_u32_e32 v82, v69, v119
	ds_read_b128 v[82:85], v82
	global_store_dwordx2 v[66:67], v[86:87], off offset:352
	v_mfma_f32_16x16x32_bf16 v[70:73], v[70:73], v[32:35], 0
	s_waitcnt lgkmcnt(1)
	v_mfma_f32_16x16x32_bf16 v[78:81], v[74:77], v[4:7], v[78:81]
	v_mfma_f32_16x16x32_bf16 v[70:73], v[74:77], v[36:39], v[70:73]
	v_add_u32_e32 v74, v69, v118
	ds_read_b128 v[74:77], v74
	s_waitcnt lgkmcnt(0)
; #define LAS __attribute__((address_space(3)))
; __device__ __forceinline__ unsigned cvtpk(float lo, float hi) { unsigned r; asm volatile("v_cvt_pk_bf16_f32 %0, %1, %2" : "=v"(r) : "v"(lo), "v"(hi)); return r; }
; template <class Sched> __device__ __forceinline__ void att_phase(LAS unsigned char* lds, const bf16_t* Kl, const bf16_t* Vl, const bf16_t* Qb, bf16_t* Ob, const Sched& S, int tid) {
;     ...
; #pragma unroll
;         for (int db = 0; db < 16; ++db) {
;             f32x4 o0 = (f32x4){0.f, 0.f, 0.f, 0.f}, o1 = o0;
; #pragma unroll
;             for (int t = 0; t < 8; ++t) { const bf16x8_t af = *(const LAS bf16x8_t*)(fbase + db * 8192 + (((4 * t + kg) ^ j) << 4));
;                 o0 = __builtin_amdgcn_mfma_f32_16x16x32_bf16(af, pf[0][t], o0, 0, 0, 0); o1 = __builtin_amdgcn_mfma_f32_16x16x32_bf16(af, pf[1][t], o1, 0, 0, 0); }
;             u32x2_t w; w.x = cvtpk(o0[0] * inv[0], o0[1] * inv[0]); w.y = cvtpk(o0[2] * inv[0], o0[3] * inv[0]);
;             *(u32x2_t*)(orow + 16 * db + 4 * kg) = w;
;             w.x = cvtpk(o1[0] * inv[1], o1[1] * inv[1]); w.y = cvtpk(o1[2] * inv[1], o1[3] * inv[1]);
;             *(u32x2_t*)(orow + (size_t)128 * 1024 + 16 * db + 4 * kg) = w;
;         }
	v_mfma_f32_16x16x32_bf16 v[78:81], v[74:77], v[8:11], v[78:81]
	v_mfma_f32_16x16x32_bf16 v[70:73], v[74:77], v[40:43], v[70:73]
	v_mfma_f32_16x16x32_bf16 v[74:77], v[82:85], v[12:15], v[78:81]
	s_nop 5
	v_add_u32_e32 v78, v69, v120
	ds_read_b128 v[78:81], v78
	v_mfma_f32_16x16x32_bf16 v[70:73], v[82:85], v[44:47], v[70:73]
	v_add_u32_e32 v82, v69, v121
	ds_read_b128 v[82:85], v82
	s_waitcnt lgkmcnt(1)
	v_mfma_f32_16x16x32_bf16 v[74:77], v[78:81], v[16:19], v[74:77]
	v_mfma_f32_16x16x32_bf16 v[70:73], v[78:81], v[48:51], v[70:73]
	v_add_u32_e32 v78, v69, v122
	ds_read_b128 v[78:81], v78
	v_add_u32_e32 v69, v69, v123
	s_waitcnt lgkmcnt(1)
	v_mfma_f32_16x16x32_bf16 v[74:77], v[82:85], v[20:23], v[74:77]
	v_mfma_f32_16x16x32_bf16 v[70:73], v[82:85], v[52:55], v[70:73]
	ds_read_b128 v[82:85], v69
	s_waitcnt lgkmcnt(1)
	v_mfma_f32_16x16x32_bf16 v[74:77], v[78:81], v[24:27], v[74:77]
	v_mfma_f32_16x16x32_bf16 v[70:73], v[78:81], v[56:59], v[70:73]
	s_waitcnt lgkmcnt(0)
	v_mfma_f32_16x16x32_bf16 v[74:77], v[82:85], v[28:31], v[74:77]
	v_mfma_f32_16x16x32_bf16 v[70:73], v[82:85], v[60:63], v[70:73]
	s_nop 6
	v_mul_f32_e32 v69, v140, v74
	v_mul_f32_e32 v74, v140, v75
	v_cvt_pk_bf16_f32 v74, v69, v74
	v_mul_f32_e32 v69, v140, v76
	v_mul_f32_e32 v75, v140, v77
	v_cvt_pk_bf16_f32 v75, v69, v75
	v_mul_f32_e32 v69, v68, v70
	global_store_dwordx2 v[64:65], v[74:75], off offset:384
	v_mul_f32_e32 v70, v68, v71
	v_cvt_pk_bf16_f32 v86, v69, v70
	v_mul_f32_e32 v69, v68, v72
	v_mul_f32_e32 v70, v68, v73
	v_cvt_pk_bf16_f32 v87, v69, v70
	v_add_u32_e32 v69, 0x1a000, v115
	v_add_u32_e32 v70, v69, v116
	ds_read_b128 v[70:73], v70
	v_add_u32_e32 v74, v69, v117
	ds_read_b128 v[74:77], v74
	s_waitcnt lgkmcnt(1)
	v_mfma_f32_16x16x32_bf16 v[78:81], v[70:73], v[0:3], 0
	v_add_u32_e32 v82, v69, v119
	ds_read_b128 v[82:85], v82
	global_store_dwordx2 v[66:67], v[86:87], off offset:384
	v_mfma_f32_16x16x32_bf16 v[70:73], v[70:73], v[32:35], 0
	s_waitcnt lgkmcnt(1)
	v_mfma_f32_16x16x32_bf16 v[78:81], v[74:77], v[4:7], v[78:81]
	v_mfma_f32_16x16x32_bf16 v[70:73], v[74:77], v[36:39], v[70:73]
	v_add_u32_e32 v74, v69, v118
	ds_read_b128 v[74:77], v74
	s_waitcnt lgkmcnt(0)
	v_mfma_f32_16x16x32_bf16 v[78:81], v[74:77], v[8:11], v[78:81]
	v_mfma_f32_16x16x32_bf16 v[70:73], v[74:77], v[40:43], v[70:73]
	v_mfma_f32_16x16x32_bf16 v[74:77], v[82:85], v[12:15], v[78:81]
	s_nop 5
	v_add_u32_e32 v78, v69, v120
	ds_read_b128 v[78:81], v78
	v_mfma_f32_16x16x32_bf16 v[70:73], v[82:85], v[44:47], v[70:73]
	v_add_u32_e32 v82, v69, v121
	ds_read_b128 v[82:85], v82
	s_waitcnt lgkmcnt(1)
	v_mfma_f32_16x16x32_bf16 v[74:77], v[78:81], v[16:19], v[74:77]
	v_mfma_f32_16x16x32_bf16 v[70:73], v[78:81], v[48:51], v[70:73]
	v_add_u32_e32 v78, v69, v122
	ds_read_b128 v[78:81], v78
	v_add_u32_e32 v69, v69, v123
	s_waitcnt lgkmcnt(1)
	v_mfma_f32_16x16x32_bf16 v[74:77], v[82:85], v[20:23], v[74:77]
	v_mfma_f32_16x16x32_bf16 v[70:73], v[82:85], v[52:55], v[70:73]
	ds_read_b128 v[82:85], v69
	s_waitcnt lgkmcnt(1)
	v_mfma_f32_16x16x32_bf16 v[74:77], v[78:81], v[24:27], v[74:77]
	v_mfma_f32_16x16x32_bf16 v[70:73], v[78:81], v[56:59], v[70:73]
	s_waitcnt lgkmcnt(0)
	v_mfma_f32_16x16x32_bf16 v[74:77], v[82:85], v[28:31], v[74:77]
	v_mfma_f32_16x16x32_bf16 v[70:73], v[82:85], v[60:63], v[70:73]
	s_nop 6
	v_mul_f32_e32 v69, v140, v74
	v_mul_f32_e32 v74, v140, v75
	v_cvt_pk_bf16_f32 v74, v69, v74
	v_mul_f32_e32 v69, v140, v76
	v_mul_f32_e32 v75, v140, v77
	v_cvt_pk_bf16_f32 v75, v69, v75
	v_mul_f32_e32 v69, v68, v70
	global_store_dwordx2 v[64:65], v[74:75], off offset:416
	v_mul_f32_e32 v70, v68, v71
	v_cvt_pk_bf16_f32 v86, v69, v70
	v_mul_f32_e32 v69, v68, v72
	v_mul_f32_e32 v70, v68, v73
	v_cvt_pk_bf16_f32 v87, v69, v70
	v_add_u32_e32 v69, 0x1c000, v115
	v_add_u32_e32 v70, v69, v116
	ds_read_b128 v[70:73], v70
	v_add_u32_e32 v74, v69, v117
	ds_read_b128 v[74:77], v74
	s_waitcnt lgkmcnt(1)
	v_mfma_f32_16x16x32_bf16 v[78:81], v[70:73], v[0:3], 0
	v_add_u32_e32 v82, v69, v119
	ds_read_b128 v[82:85], v82
	global_store_dwordx2 v[66:67], v[86:87], off offset:416
	v_mfma_f32_16x16x32_bf16 v[70:73], v[70:73], v[32:35], 0
	s_waitcnt lgkmcnt(1)
; #define LAS __attribute__((address_space(3)))
; __device__ __forceinline__ unsigned cvtpk(float lo, float hi) { unsigned r; asm volatile("v_cvt_pk_bf16_f32 %0, %1, %2" : "=v"(r) : "v"(lo), "v"(hi)); return r; }
; template <class Sched> __device__ __forceinline__ void att_phase(LAS unsigned char* lds, const bf16_t* Kl, const bf16_t* Vl, const bf16_t* Qb, bf16_t* Ob, const Sched& S, int tid) {
;     ...
; #pragma unroll
;         for (int db = 0; db < 16; ++db) {
;             f32x4 o0 = (f32x4){0.f, 0.f, 0.f, 0.f}, o1 = o0;
; #pragma unroll
;             for (int t = 0; t < 8; ++t) { const bf16x8_t af = *(const LAS bf16x8_t*)(fbase + db * 8192 + (((4 * t + kg) ^ j) << 4));
;                 o0 = __builtin_amdgcn_mfma_f32_16x16x32_bf16(af, pf[0][t], o0, 0, 0, 0); o1 = __builtin_amdgcn_mfma_f32_16x16x32_bf16(af, pf[1][t], o1, 0, 0, 0); }
;             u32x2_t w; w.x = cvtpk(o0[0] * inv[0], o0[1] * inv[0]); w.y = cvtpk(o0[2] * inv[0], o0[3] * inv[0]);
;             *(u32x2_t*)(orow + 16 * db + 4 * kg) = w;
;             w.x = cvtpk(o1[0] * inv[1], o1[1] * inv[1]); w.y = cvtpk(o1[2] * inv[1], o1[3] * inv[1]);
;             *(u32x2_t*)(orow + (size_t)128 * 1024 + 16 * db + 4 * kg) = w;
;         }
;         __syncthreads();
	v_mfma_f32_16x16x32_bf16 v[78:81], v[74:77], v[4:7], v[78:81]
	v_mfma_f32_16x16x32_bf16 v[70:73], v[74:77], v[36:39], v[70:73]
	v_add_u32_e32 v74, v69, v118
	ds_read_b128 v[74:77], v74
	s_waitcnt lgkmcnt(0)
	v_mfma_f32_16x16x32_bf16 v[78:81], v[74:77], v[8:11], v[78:81]
	v_mfma_f32_16x16x32_bf16 v[70:73], v[74:77], v[40:43], v[70:73]
	v_mfma_f32_16x16x32_bf16 v[74:77], v[82:85], v[12:15], v[78:81]
	s_nop 5
	v_add_u32_e32 v78, v69, v120
	ds_read_b128 v[78:81], v78
	v_mfma_f32_16x16x32_bf16 v[70:73], v[82:85], v[44:47], v[70:73]
	v_add_u32_e32 v82, v69, v121
	ds_read_b128 v[82:85], v82
	s_waitcnt lgkmcnt(1)
	v_mfma_f32_16x16x32_bf16 v[74:77], v[78:81], v[16:19], v[74:77]
	v_mfma_f32_16x16x32_bf16 v[70:73], v[78:81], v[48:51], v[70:73]
	v_add_u32_e32 v78, v69, v122
	ds_read_b128 v[78:81], v78
	v_add_u32_e32 v69, v69, v123
	s_waitcnt lgkmcnt(1)
	v_mfma_f32_16x16x32_bf16 v[74:77], v[82:85], v[20:23], v[74:77]
	v_mfma_f32_16x16x32_bf16 v[70:73], v[82:85], v[52:55], v[70:73]
	ds_read_b128 v[82:85], v69
	s_waitcnt lgkmcnt(1)
	v_mfma_f32_16x16x32_bf16 v[74:77], v[78:81], v[24:27], v[74:77]
	v_mfma_f32_16x16x32_bf16 v[70:73], v[78:81], v[56:59], v[70:73]
	s_waitcnt lgkmcnt(0)
	v_mfma_f32_16x16x32_bf16 v[74:77], v[82:85], v[28:31], v[74:77]
	v_mfma_f32_16x16x32_bf16 v[70:73], v[82:85], v[60:63], v[70:73]
	s_nop 6
	v_mul_f32_e32 v69, v140, v74
	v_mul_f32_e32 v74, v140, v75
	v_cvt_pk_bf16_f32 v74, v69, v74
	v_mul_f32_e32 v69, v140, v76
	v_mul_f32_e32 v75, v140, v77
	v_cvt_pk_bf16_f32 v75, v69, v75
	v_mul_f32_e32 v69, v68, v70
	global_store_dwordx2 v[64:65], v[74:75], off offset:448
	v_mul_f32_e32 v70, v68, v71
	v_cvt_pk_bf16_f32 v78, v69, v70
	v_mul_f32_e32 v69, v68, v72
	v_mul_f32_e32 v70, v68, v73
	v_cvt_pk_bf16_f32 v79, v69, v70
	v_add_u32_e32 v69, 0x1e000, v115
	v_add_u32_e32 v70, v69, v116
	ds_read_b128 v[70:73], v70
	v_add_u32_e32 v74, v69, v117
	ds_read_b128 v[74:77], v74
	s_waitcnt lgkmcnt(1)
	v_mfma_f32_16x16x32_bf16 v[0:3], v[70:73], v[0:3], 0
	global_store_dwordx2 v[66:67], v[78:79], off offset:448
	v_mfma_f32_16x16x32_bf16 v[32:35], v[70:73], v[32:35], 0
	s_waitcnt lgkmcnt(0)
	v_mfma_f32_16x16x32_bf16 v[0:3], v[74:77], v[4:7], v[0:3]
	v_mfma_f32_16x16x32_bf16 v[4:7], v[74:77], v[36:39], v[32:35]
	v_add_u32_e32 v36, v69, v119
	ds_read_b128 v[36:39], v36
	s_nop 2
	v_add_u32_e32 v32, v69, v118
	ds_read_b128 v[32:35], v32
	s_waitcnt lgkmcnt(0)
	v_mfma_f32_16x16x32_bf16 v[0:3], v[32:35], v[8:11], v[0:3]
	v_add_u32_e32 v8, v69, v120
	ds_read_b128 v[8:11], v8
	v_mfma_f32_16x16x32_bf16 v[4:7], v[32:35], v[40:43], v[4:7]
	v_mfma_f32_16x16x32_bf16 v[0:3], v[36:39], v[12:15], v[0:3]
	v_add_u32_e32 v12, v69, v121
	ds_read_b128 v[12:15], v12
	v_mfma_f32_16x16x32_bf16 v[4:7], v[36:39], v[44:47], v[4:7]
	s_waitcnt lgkmcnt(1)
	v_mfma_f32_16x16x32_bf16 v[0:3], v[8:11], v[16:19], v[0:3]
	v_add_u32_e32 v16, v69, v122
	v_mfma_f32_16x16x32_bf16 v[4:7], v[8:11], v[48:51], v[4:7]
	ds_read_b128 v[8:11], v16
	v_add_u32_e32 v16, v69, v123
	ds_read_b128 v[16:19], v16
	s_waitcnt lgkmcnt(2)
	v_mfma_f32_16x16x32_bf16 v[0:3], v[12:15], v[20:23], v[0:3]
	s_waitcnt lgkmcnt(1)
	v_mfma_f32_16x16x32_bf16 v[0:3], v[8:11], v[24:27], v[0:3]
	v_mfma_f32_16x16x32_bf16 v[4:7], v[12:15], v[52:55], v[4:7]
	s_waitcnt lgkmcnt(0)
	v_mfma_f32_16x16x32_bf16 v[0:3], v[16:19], v[28:31], v[0:3]
	v_mfma_f32_16x16x32_bf16 v[4:7], v[8:11], v[56:59], v[4:7]
	s_nop 6
	v_mul_f32_e32 v0, v140, v0
	v_mul_f32_e32 v1, v140, v1
	v_cvt_pk_bf16_f32 v0, v0, v1
	v_mul_f32_e32 v1, v140, v2
	v_mul_f32_e32 v2, v140, v3
	v_cvt_pk_bf16_f32 v1, v1, v2
	global_store_dwordx2 v[64:65], v[0:1], off offset:480
	v_mfma_f32_16x16x32_bf16 v[0:3], v[16:19], v[60:63], v[4:7]
	s_nop 7
	v_mul_f32_e32 v0, v68, v0
	v_mul_f32_e32 v1, v68, v1
	v_cvt_pk_bf16_f32 v0, v0, v1
	v_mul_f32_e32 v1, v68, v2
	v_mul_f32_e32 v2, v68, v3
	v_cvt_pk_bf16_f32 v1, v1, v2
	global_store_dwordx2 v[66:67], v[0:1], off offset:480
	s_barrier
